# RWKV chain v3: early LDS reads with counted waits and packed f32 FMA ops
# speedup vs baseline: 1.0706x; 1.0202x over previous
; DEVI void rw_chain_task(const Params& p, int l, int seq, int head, int quarter, char* smem) {
;     ...
;     for (int c = 0; c < nch; c += 4) {
;       lds_barrier();
;       RW_STORE(R1, B1);
;       RW_LOAD(R1, c + 5);
;       RW_COMPUTE(B0, c);
;       lds_barrier();
;       RW_STORE(R2, B0);
;       RW_LOAD(R2, c + 6);
;       RW_COMPUTE(B1, c + 1);
;       lds_barrier();
;       RW_STORE(R3, B1);
;       RW_LOAD(R3, c + 7);
;       RW_COMPUTE(B0, c + 2);
;       lds_barrier();
;       RW_STORE(R0, B0);
;       RW_LOAD(R0, c + 8);
;       RW_COMPUTE(B1, c + 3);
;     }
.Lrwc_loop:
	s_waitcnt lgkmcnt(0)
	s_barrier
	s_mov_b32 vcc_lo, s42
	s_mov_b32 s42, s43
	s_mov_b32 s43, s45
	s_mov_b32 s45, vcc_lo
	v_add_u32_e32 v156, s42, v162
	v_add_u32_e32 v157, s42, v163
	v_add_u32_e32 v155, s45, v164
	v_add_u32_e32 v165, s45, v167
	v_add_u32_e32 v166, s45, v168
	s_waitcnt lgkmcnt(0)
	ds_read_b128 v[28:31], v156 offset:1408
	ds_read_b128 v[36:39], v156 offset:1440
	ds_read_u16_d16_hi v48, v157 offset:1408
	ds_read_b128 v[44:47], v156 offset:1472
	ds_read_b128 v[32:35], v156 offset:1424
	v_pk_mul_f32 v[172:173], v[68:69], v[4:5]
	v_pk_mul_f32 v[178:179], v[68:69], v[40:41]
	v_pk_fma_f32 v[172:173], v[70:71], v[6:7], v[172:173]
	v_pk_fma_f32 v[178:179], v[70:71], v[42:43], v[178:179]
	v_add_f32_e32 v172, v172, v173
	v_add_f32_e32 v178, v178, v179
	v_pk_mul_f32 v[52:53], v[24:25], v[12:13] op_sel_hi:[0,1]
	ds_read_b128 v[40:43], v156 offset:1456
	v_add_f32_dpp v172, v172, v172 row_ror:8 row_mask:0xf bank_mask:0xf bound_ctrl:1
	v_pk_mul_f32 v[54:55], v[24:25], v[14:15] op_sel_hi:[0,1]
	v_add_f32_dpp v178, v178, v178 row_ror:8 row_mask:0xf bank_mask:0xf bound_ctrl:1
	v_pk_fma_f32 v[56:57], v[68:69], v[20:21], v[52:53]
	v_add_f32_dpp v172, v172, v172 row_ror:4 row_mask:0xf bank_mask:0xf bound_ctrl:1
	v_pk_fma_f32 v[58:59], v[70:71], v[22:23], v[54:55]
	v_add_f32_dpp v178, v178, v178 row_ror:4 row_mask:0xf bank_mask:0xf bound_ctrl:1
	v_add_f32_dpp v172, v172, v172 row_ror:2 row_mask:0xf bank_mask:0xf bound_ctrl:1
	s_nop 0
	v_add_f32_dpp v178, v178, v178 row_ror:2 row_mask:0xf bank_mask:0xf bound_ctrl:1
	v_add_f32_dpp v172, v172, v172 row_ror:1 row_mask:0xf bank_mask:0xf bound_ctrl:1
	s_nop 0
	v_add_f32_dpp v178, v178, v178 row_ror:1 row_mask:0xf bank_mask:0xf bound_ctrl:1
	v_pk_fma_f32 v[68:69], v[172:173], v[8:9], v[56:57] op_sel_hi:[0,1,1] neg_lo:[1,0,0] neg_hi:[1,0,0]
	v_pk_fma_f32 v[70:71], v[172:173], v[10:11], v[58:59] op_sel_hi:[0,1,1] neg_lo:[1,0,0] neg_hi:[1,0,0]
	v_cndmask_b32_e64 v60, v60, v178, s[36:37]
	s_cmp_eq_u32 s41, 0
	s_cbranch_scc1 .Lrwc_nostore
	v_bfe_u32 v61, v60, 16, 1
	v_add3_u32 v61, v60, v61, s33
	global_store_short_d16_hi v[160:161], v61, off
	v_lshl_add_u64 v[160:161], v[160:161], 0, s[46:47]
.Lrwc_nostore:
	s_waitcnt lgkmcnt(0)
	ds_read_b128 v[4:7], v156 offset:2816
	ds_read_b128 v[12:15], v156 offset:2848
	ds_read_u16_d16_hi v24, v157 offset:2816
	ds_read_b128 v[20:23], v156 offset:2880
	ds_read_b128 v[8:11], v156 offset:2832
	v_pk_mul_f32 v[174:175], v[68:69], v[28:29]
	v_pk_mul_f32 v[176:177], v[68:69], v[16:17]
	v_pk_fma_f32 v[174:175], v[70:71], v[30:31], v[174:175]
	v_pk_fma_f32 v[176:177], v[70:71], v[18:19], v[176:177]
	v_add_f32_e32 v174, v174, v175
	v_add_f32_e32 v176, v176, v177
	v_pk_mul_f32 v[52:53], v[48:49], v[36:37] op_sel_hi:[0,1]
	ds_read_b128 v[16:19], v156 offset:2864
	v_add_f32_dpp v174, v174, v174 row_ror:8 row_mask:0xf bank_mask:0xf bound_ctrl:1
	v_pk_mul_f32 v[54:55], v[48:49], v[38:39] op_sel_hi:[0,1]
	v_add_f32_dpp v176, v176, v176 row_ror:8 row_mask:0xf bank_mask:0xf bound_ctrl:1
	v_pk_fma_f32 v[56:57], v[68:69], v[44:45], v[52:53]
	v_add_f32_dpp v174, v174, v174 row_ror:4 row_mask:0xf bank_mask:0xf bound_ctrl:1
	v_pk_fma_f32 v[58:59], v[70:71], v[46:47], v[54:55]
	v_add_f32_dpp v176, v176, v176 row_ror:4 row_mask:0xf bank_mask:0xf bound_ctrl:1
	s_waitcnt vmcnt(12)
	v_add_f32_dpp v174, v174, v174 row_ror:2 row_mask:0xf bank_mask:0xf bound_ctrl:1
	v_lshlrev_b32_e32 v136, 16, v104
	v_add_f32_dpp v176, v176, v176 row_ror:2 row_mask:0xf bank_mask:0xf bound_ctrl:1
	v_and_b32_e32 v137, 0xffff0000, v104
	v_add_f32_dpp v174, v174, v174 row_ror:1 row_mask:0xf bank_mask:0xf bound_ctrl:1
	v_add_f32_dpp v176, v176, v176 row_ror:1 row_mask:0xf bank_mask:0xf bound_ctrl:1
	v_pk_fma_f32 v[68:69], v[174:175], v[32:33], v[56:57] op_sel_hi:[0,1,1] neg_lo:[1,0,0] neg_hi:[1,0,0]
	v_pk_fma_f32 v[70:71], v[174:175], v[34:35], v[58:59] op_sel_hi:[0,1,1] neg_lo:[1,0,0] neg_hi:[1,0,0]
	v_cndmask_b32_e64 v60, v60, v176, s[4:5]
	s_waitcnt lgkmcnt(0)
	ds_read_b128 v[28:31], v156 offset:4224
	ds_read_b128 v[36:39], v156 offset:4256
	ds_read_u16_d16_hi v48, v157 offset:4224
	ds_read_b128 v[44:47], v156 offset:4288
	ds_read_b128 v[32:35], v156 offset:4240
	v_pk_mul_f32 v[172:173], v[68:69], v[4:5]
	v_pk_mul_f32 v[178:179], v[68:69], v[40:41]
	v_pk_fma_f32 v[172:173], v[70:71], v[6:7], v[172:173]
	v_pk_fma_f32 v[178:179], v[70:71], v[42:43], v[178:179]
	v_add_f32_e32 v172, v172, v173
	v_add_f32_e32 v178, v178, v179
	v_pk_mul_f32 v[52:53], v[24:25], v[12:13] op_sel_hi:[0,1]
	ds_read_b128 v[40:43], v156 offset:4272
	v_add_f32_dpp v172, v172, v172 row_ror:8 row_mask:0xf bank_mask:0xf bound_ctrl:1
	v_pk_mul_f32 v[54:55], v[24:25], v[14:15] op_sel_hi:[0,1]
	v_add_f32_dpp v178, v178, v178 row_ror:8 row_mask:0xf bank_mask:0xf bound_ctrl:1
	v_pk_fma_f32 v[56:57], v[68:69], v[20:21], v[52:53]
	v_add_f32_dpp v172, v172, v172 row_ror:4 row_mask:0xf bank_mask:0xf bound_ctrl:1
	v_pk_fma_f32 v[58:59], v[70:71], v[22:23], v[54:55]
	v_add_f32_dpp v178, v178, v178 row_ror:4 row_mask:0xf bank_mask:0xf bound_ctrl:1
	v_lshlrev_b32_e32 v138, 16, v105
	v_add_f32_dpp v172, v172, v172 row_ror:2 row_mask:0xf bank_mask:0xf bound_ctrl:1
	v_and_b32_e32 v139, 0xffff0000, v105
	v_add_f32_dpp v178, v178, v178 row_ror:2 row_mask:0xf bank_mask:0xf bound_ctrl:1
	v_lshlrev_b32_e32 v140, 16, v106
	v_add_f32_dpp v172, v172, v172 row_ror:1 row_mask:0xf bank_mask:0xf bound_ctrl:1
	v_add_f32_dpp v178, v178, v178 row_ror:1 row_mask:0xf bank_mask:0xf bound_ctrl:1
	v_pk_fma_f32 v[68:69], v[172:173], v[8:9], v[56:57] op_sel_hi:[0,1,1] neg_lo:[1,0,0] neg_hi:[1,0,0]
	v_pk_fma_f32 v[70:71], v[172:173], v[10:11], v[58:59] op_sel_hi:[0,1,1] neg_lo:[1,0,0] neg_hi:[1,0,0]
	v_cndmask_b32_e64 v60, v60, v178, s[6:7]
	s_waitcnt lgkmcnt(0)
	ds_read_b128 v[4:7], v156 offset:5632
	ds_read_b128 v[12:15], v156 offset:5664
	ds_read_u16_d16_hi v24, v157 offset:5632
	ds_read_b128 v[20:23], v156 offset:5696
	ds_read_b128 v[8:11], v156 offset:5648
	v_pk_mul_f32 v[174:175], v[68:69], v[28:29]
	v_pk_mul_f32 v[176:177], v[68:69], v[16:17]
	v_pk_fma_f32 v[174:175], v[70:71], v[30:31], v[174:175]
	v_pk_fma_f32 v[176:177], v[70:71], v[18:19], v[176:177]
	v_add_f32_e32 v174, v174, v175
	v_add_f32_e32 v176, v176, v177
	v_pk_mul_f32 v[52:53], v[48:49], v[36:37] op_sel_hi:[0,1]
	ds_read_b128 v[16:19], v156 offset:5680
	v_add_f32_dpp v174, v174, v174 row_ror:8 row_mask:0xf bank_mask:0xf bound_ctrl:1
	v_pk_mul_f32 v[54:55], v[48:49], v[38:39] op_sel_hi:[0,1]
	v_add_f32_dpp v176, v176, v176 row_ror:8 row_mask:0xf bank_mask:0xf bound_ctrl:1
	v_pk_fma_f32 v[56:57], v[68:69], v[44:45], v[52:53]
	v_add_f32_dpp v174, v174, v174 row_ror:4 row_mask:0xf bank_mask:0xf bound_ctrl:1
	v_pk_fma_f32 v[58:59], v[70:71], v[46:47], v[54:55]
	v_add_f32_dpp v176, v176, v176 row_ror:4 row_mask:0xf bank_mask:0xf bound_ctrl:1
	v_and_b32_e32 v141, 0xffff0000, v106
	v_add_f32_dpp v174, v174, v174 row_ror:2 row_mask:0xf bank_mask:0xf bound_ctrl:1
	v_lshlrev_b32_e32 v142, 16, v107
	v_add_f32_dpp v176, v176, v176 row_ror:2 row_mask:0xf bank_mask:0xf bound_ctrl:1
	v_and_b32_e32 v143, 0xffff0000, v107
	v_add_f32_dpp v174, v174, v174 row_ror:1 row_mask:0xf bank_mask:0xf bound_ctrl:1
	v_add_f32_dpp v176, v176, v176 row_ror:1 row_mask:0xf bank_mask:0xf bound_ctrl:1
	v_pk_fma_f32 v[68:69], v[174:175], v[32:33], v[56:57] op_sel_hi:[0,1,1] neg_lo:[1,0,0] neg_hi:[1,0,0]
	v_pk_fma_f32 v[70:71], v[174:175], v[34:35], v[58:59] op_sel_hi:[0,1,1] neg_lo:[1,0,0] neg_hi:[1,0,0]
	v_cndmask_b32_e64 v60, v60, v176, s[8:9]
	s_waitcnt lgkmcnt(0)
	ds_read_b128 v[28:31], v156 offset:7040
	ds_read_b128 v[36:39], v156 offset:7072
	ds_read_u16_d16_hi v48, v157 offset:7040
	ds_read_b128 v[44:47], v156 offset:7104
	ds_read_b128 v[32:35], v156 offset:7056
	v_pk_mul_f32 v[172:173], v[68:69], v[4:5]
	v_pk_mul_f32 v[178:179], v[68:69], v[40:41]
	v_pk_fma_f32 v[172:173], v[70:71], v[6:7], v[172:173]
	v_pk_fma_f32 v[178:179], v[70:71], v[42:43], v[178:179]
	v_add_f32_e32 v172, v172, v173
	v_add_f32_e32 v178, v178, v179
	v_pk_mul_f32 v[52:53], v[24:25], v[12:13] op_sel_hi:[0,1]
	ds_read_b128 v[40:43], v156 offset:7088
	v_add_f32_dpp v172, v172, v172 row_ror:8 row_mask:0xf bank_mask:0xf bound_ctrl:1
	v_pk_mul_f32 v[54:55], v[24:25], v[14:15] op_sel_hi:[0,1]
	v_add_f32_dpp v178, v178, v178 row_ror:8 row_mask:0xf bank_mask:0xf bound_ctrl:1
	v_pk_fma_f32 v[56:57], v[68:69], v[20:21], v[52:53]
	v_add_f32_dpp v172, v172, v172 row_ror:4 row_mask:0xf bank_mask:0xf bound_ctrl:1
	v_pk_fma_f32 v[58:59], v[70:71], v[22:23], v[54:55]
	v_add_f32_dpp v178, v178, v178 row_ror:4 row_mask:0xf bank_mask:0xf bound_ctrl:1
	ds_write_b128 v155, v[136:139] offset:0
	v_add_f32_dpp v172, v172, v172 row_ror:2 row_mask:0xf bank_mask:0xf bound_ctrl:1
	ds_write_b128 v155, v[140:143] offset:80
	v_add_f32_dpp v178, v178, v178 row_ror:2 row_mask:0xf bank_mask:0xf bound_ctrl:1
	v_lshlrev_b32_e32 v136, 16, v108
	v_add_f32_dpp v172, v172, v172 row_ror:1 row_mask:0xf bank_mask:0xf bound_ctrl:1
	v_add_f32_dpp v178, v178, v178 row_ror:1 row_mask:0xf bank_mask:0xf bound_ctrl:1
	v_pk_fma_f32 v[68:69], v[172:173], v[8:9], v[56:57] op_sel_hi:[0,1,1] neg_lo:[1,0,0] neg_hi:[1,0,0]
	v_pk_fma_f32 v[70:71], v[172:173], v[10:11], v[58:59] op_sel_hi:[0,1,1] neg_lo:[1,0,0] neg_hi:[1,0,0]
	v_cndmask_b32_e64 v60, v60, v178, s[10:11]
	s_waitcnt lgkmcnt(2)
	ds_read_b128 v[4:7], v156 offset:8448
	ds_read_b128 v[12:15], v156 offset:8480
	ds_read_u16_d16_hi v24, v157 offset:8448
	ds_read_b128 v[20:23], v156 offset:8512
	ds_read_b128 v[8:11], v156 offset:8464
	v_pk_mul_f32 v[174:175], v[68:69], v[28:29]
	v_pk_mul_f32 v[176:177], v[68:69], v[16:17]
	v_pk_fma_f32 v[174:175], v[70:71], v[30:31], v[174:175]
	v_pk_fma_f32 v[176:177], v[70:71], v[18:19], v[176:177]
	v_add_f32_e32 v174, v174, v175
	v_add_f32_e32 v176, v176, v177
	v_pk_mul_f32 v[52:53], v[48:49], v[36:37] op_sel_hi:[0,1]
	ds_read_b128 v[16:19], v156 offset:8496
	v_add_f32_dpp v174, v174, v174 row_ror:8 row_mask:0xf bank_mask:0xf bound_ctrl:1
	v_pk_mul_f32 v[54:55], v[48:49], v[38:39] op_sel_hi:[0,1]
	v_add_f32_dpp v176, v176, v176 row_ror:8 row_mask:0xf bank_mask:0xf bound_ctrl:1
	v_pk_fma_f32 v[56:57], v[68:69], v[44:45], v[52:53]
	v_add_f32_dpp v174, v174, v174 row_ror:4 row_mask:0xf bank_mask:0xf bound_ctrl:1
	v_pk_fma_f32 v[58:59], v[70:71], v[46:47], v[54:55]
	v_add_f32_dpp v176, v176, v176 row_ror:4 row_mask:0xf bank_mask:0xf bound_ctrl:1
	v_and_b32_e32 v137, 0xffff0000, v108
	v_add_f32_dpp v174, v174, v174 row_ror:2 row_mask:0xf bank_mask:0xf bound_ctrl:1
	v_lshlrev_b32_e32 v138, 16, v109
	v_add_f32_dpp v176, v176, v176 row_ror:2 row_mask:0xf bank_mask:0xf bound_ctrl:1
	v_and_b32_e32 v139, 0xffff0000, v109
	v_add_f32_dpp v174, v174, v174 row_ror:1 row_mask:0xf bank_mask:0xf bound_ctrl:1
	v_add_f32_dpp v176, v176, v176 row_ror:1 row_mask:0xf bank_mask:0xf bound_ctrl:1
	v_pk_fma_f32 v[68:69], v[174:175], v[32:33], v[56:57] op_sel_hi:[0,1,1] neg_lo:[1,0,0] neg_hi:[1,0,0]
	v_pk_fma_f32 v[70:71], v[174:175], v[34:35], v[58:59] op_sel_hi:[0,1,1] neg_lo:[1,0,0] neg_hi:[1,0,0]
	v_cndmask_b32_e64 v60, v60, v176, s[12:13]
	s_waitcnt lgkmcnt(0)
	ds_read_b128 v[28:31], v156 offset:9856
	ds_read_b128 v[36:39], v156 offset:9888
	ds_read_u16_d16_hi v48, v157 offset:9856
	ds_read_b128 v[44:47], v156 offset:9920
	ds_read_b128 v[32:35], v156 offset:9872
	v_pk_mul_f32 v[172:173], v[68:69], v[4:5]
	v_pk_mul_f32 v[178:179], v[68:69], v[40:41]
	v_pk_fma_f32 v[172:173], v[70:71], v[6:7], v[172:173]
	v_pk_fma_f32 v[178:179], v[70:71], v[42:43], v[178:179]
	v_add_f32_e32 v172, v172, v173
	v_add_f32_e32 v178, v178, v179
	v_pk_mul_f32 v[52:53], v[24:25], v[12:13] op_sel_hi:[0,1]
	ds_read_b128 v[40:43], v156 offset:9904
	v_add_f32_dpp v172, v172, v172 row_ror:8 row_mask:0xf bank_mask:0xf bound_ctrl:1
	v_pk_mul_f32 v[54:55], v[24:25], v[14:15] op_sel_hi:[0,1]
	v_add_f32_dpp v178, v178, v178 row_ror:8 row_mask:0xf bank_mask:0xf bound_ctrl:1
	v_pk_fma_f32 v[56:57], v[68:69], v[20:21], v[52:53]
	v_add_f32_dpp v172, v172, v172 row_ror:4 row_mask:0xf bank_mask:0xf bound_ctrl:1
	v_pk_fma_f32 v[58:59], v[70:71], v[22:23], v[54:55]
	v_add_f32_dpp v178, v178, v178 row_ror:4 row_mask:0xf bank_mask:0xf bound_ctrl:1
	v_lshlrev_b32_e32 v140, 16, v110
	v_add_f32_dpp v172, v172, v172 row_ror:2 row_mask:0xf bank_mask:0xf bound_ctrl:1
	v_and_b32_e32 v141, 0xffff0000, v110
	v_add_f32_dpp v178, v178, v178 row_ror:2 row_mask:0xf bank_mask:0xf bound_ctrl:1
	v_lshlrev_b32_e32 v142, 16, v111
	v_add_f32_dpp v172, v172, v172 row_ror:1 row_mask:0xf bank_mask:0xf bound_ctrl:1
	v_add_f32_dpp v178, v178, v178 row_ror:1 row_mask:0xf bank_mask:0xf bound_ctrl:1
	v_pk_fma_f32 v[68:69], v[172:173], v[8:9], v[56:57] op_sel_hi:[0,1,1] neg_lo:[1,0,0] neg_hi:[1,0,0]
	v_pk_fma_f32 v[70:71], v[172:173], v[10:11], v[58:59] op_sel_hi:[0,1,1] neg_lo:[1,0,0] neg_hi:[1,0,0]
	v_cndmask_b32_e64 v60, v60, v178, s[14:15]
	s_waitcnt lgkmcnt(0)
	ds_read_b128 v[4:7], v156 offset:11264
	ds_read_b128 v[12:15], v156 offset:11296
	ds_read_u16_d16_hi v24, v157 offset:11264
	ds_read_b128 v[20:23], v156 offset:11328
	ds_read_b128 v[8:11], v156 offset:11280
	v_pk_mul_f32 v[174:175], v[68:69], v[28:29]
	v_pk_mul_f32 v[176:177], v[68:69], v[16:17]
	v_pk_fma_f32 v[174:175], v[70:71], v[30:31], v[174:175]
	v_pk_fma_f32 v[176:177], v[70:71], v[18:19], v[176:177]
	v_add_f32_e32 v174, v174, v175
	v_add_f32_e32 v176, v176, v177
	v_pk_mul_f32 v[52:53], v[48:49], v[36:37] op_sel_hi:[0,1]
	ds_read_b128 v[16:19], v156 offset:11312
	v_add_f32_dpp v174, v174, v174 row_ror:8 row_mask:0xf bank_mask:0xf bound_ctrl:1
	v_pk_mul_f32 v[54:55], v[48:49], v[38:39] op_sel_hi:[0,1]
	v_add_f32_dpp v176, v176, v176 row_ror:8 row_mask:0xf bank_mask:0xf bound_ctrl:1
	v_pk_fma_f32 v[56:57], v[68:69], v[44:45], v[52:53]
	v_add_f32_dpp v174, v174, v174 row_ror:4 row_mask:0xf bank_mask:0xf bound_ctrl:1
	v_pk_fma_f32 v[58:59], v[70:71], v[46:47], v[54:55]
	v_add_f32_dpp v176, v176, v176 row_ror:4 row_mask:0xf bank_mask:0xf bound_ctrl:1
	v_and_b32_e32 v143, 0xffff0000, v111
	v_add_f32_dpp v174, v174, v174 row_ror:2 row_mask:0xf bank_mask:0xf bound_ctrl:1
	ds_write_b128 v155, v[136:139] offset:11264
	v_add_f32_dpp v176, v176, v176 row_ror:2 row_mask:0xf bank_mask:0xf bound_ctrl:1
	ds_write_b128 v155, v[140:143] offset:11344
	v_add_f32_dpp v174, v174, v174 row_ror:1 row_mask:0xf bank_mask:0xf bound_ctrl:1
	v_add_f32_dpp v176, v176, v176 row_ror:1 row_mask:0xf bank_mask:0xf bound_ctrl:1
	v_pk_fma_f32 v[68:69], v[174:175], v[32:33], v[56:57] op_sel_hi:[0,1,1] neg_lo:[1,0,0] neg_hi:[1,0,0]
	v_pk_fma_f32 v[70:71], v[174:175], v[34:35], v[58:59] op_sel_hi:[0,1,1] neg_lo:[1,0,0] neg_hi:[1,0,0]
	v_cndmask_b32_e64 v60, v60, v176, s[16:17]
	s_waitcnt lgkmcnt(2)
	ds_read_b128 v[28:31], v156 offset:12672
	ds_read_b128 v[36:39], v156 offset:12704
	ds_read_u16_d16_hi v48, v157 offset:12672
	ds_read_b128 v[44:47], v156 offset:12736
	ds_read_b128 v[32:35], v156 offset:12688
	v_pk_mul_f32 v[172:173], v[68:69], v[4:5]
	v_pk_mul_f32 v[178:179], v[68:69], v[40:41]
	v_pk_fma_f32 v[172:173], v[70:71], v[6:7], v[172:173]
	v_pk_fma_f32 v[178:179], v[70:71], v[42:43], v[178:179]
	v_add_f32_e32 v172, v172, v173
	v_add_f32_e32 v178, v178, v179
	v_pk_mul_f32 v[52:53], v[24:25], v[12:13] op_sel_hi:[0,1]
	ds_read_b128 v[40:43], v156 offset:12720
	v_add_f32_dpp v172, v172, v172 row_ror:8 row_mask:0xf bank_mask:0xf bound_ctrl:1
	v_pk_mul_f32 v[54:55], v[24:25], v[14:15] op_sel_hi:[0,1]
	v_add_f32_dpp v178, v178, v178 row_ror:8 row_mask:0xf bank_mask:0xf bound_ctrl:1
	v_pk_fma_f32 v[56:57], v[68:69], v[20:21], v[52:53]
	v_add_f32_dpp v172, v172, v172 row_ror:4 row_mask:0xf bank_mask:0xf bound_ctrl:1
	v_pk_fma_f32 v[58:59], v[70:71], v[22:23], v[54:55]
	v_add_f32_dpp v178, v178, v178 row_ror:4 row_mask:0xf bank_mask:0xf bound_ctrl:1
	ds_write_b128 v165, v[112:115]
	v_add_f32_dpp v172, v172, v172 row_ror:2 row_mask:0xf bank_mask:0xf bound_ctrl:1
	ds_write_b128 v166, v[116:119]
	v_add_f32_dpp v178, v178, v178 row_ror:2 row_mask:0xf bank_mask:0xf bound_ctrl:1
	global_load_dwordx4 v[104:107], v[144:145], off
	v_add_f32_dpp v172, v172, v172 row_ror:1 row_mask:0xf bank_mask:0xf bound_ctrl:1
	v_add_f32_dpp v178, v178, v178 row_ror:1 row_mask:0xf bank_mask:0xf bound_ctrl:1
	v_pk_fma_f32 v[68:69], v[172:173], v[8:9], v[56:57] op_sel_hi:[0,1,1] neg_lo:[1,0,0] neg_hi:[1,0,0]
	v_pk_fma_f32 v[70:71], v[172:173], v[10:11], v[58:59] op_sel_hi:[0,1,1] neg_lo:[1,0,0] neg_hi:[1,0,0]
	v_cndmask_b32_e64 v60, v60, v178, s[18:19]
	s_waitcnt lgkmcnt(2)
	ds_read_b128 v[4:7], v156 offset:14080
	ds_read_b128 v[12:15], v156 offset:14112
	ds_read_u16_d16_hi v24, v157 offset:14080
	ds_read_b128 v[20:23], v156 offset:14144
	ds_read_b128 v[8:11], v156 offset:14096
	v_pk_mul_f32 v[174:175], v[68:69], v[28:29]
	v_pk_mul_f32 v[176:177], v[68:69], v[16:17]
	v_pk_fma_f32 v[174:175], v[70:71], v[30:31], v[174:175]
	v_pk_fma_f32 v[176:177], v[70:71], v[18:19], v[176:177]
	v_add_f32_e32 v174, v174, v175
	v_add_f32_e32 v176, v176, v177
	v_pk_mul_f32 v[52:53], v[48:49], v[36:37] op_sel_hi:[0,1]
	ds_read_b128 v[16:19], v156 offset:14128
	v_add_f32_dpp v174, v174, v174 row_ror:8 row_mask:0xf bank_mask:0xf bound_ctrl:1
	v_pk_mul_f32 v[54:55], v[48:49], v[38:39] op_sel_hi:[0,1]
	v_add_f32_dpp v176, v176, v176 row_ror:8 row_mask:0xf bank_mask:0xf bound_ctrl:1
	v_pk_fma_f32 v[56:57], v[68:69], v[44:45], v[52:53]
	v_add_f32_dpp v174, v174, v174 row_ror:4 row_mask:0xf bank_mask:0xf bound_ctrl:1
	v_pk_fma_f32 v[58:59], v[70:71], v[46:47], v[54:55]
	v_add_f32_dpp v176, v176, v176 row_ror:4 row_mask:0xf bank_mask:0xf bound_ctrl:1
	global_load_dwordx4 v[108:111], v[146:147], off
	v_add_f32_dpp v174, v174, v174 row_ror:2 row_mask:0xf bank_mask:0xf bound_ctrl:1
	global_load_dwordx4 v[112:115], v[148:149], off
	v_add_f32_dpp v176, v176, v176 row_ror:2 row_mask:0xf bank_mask:0xf bound_ctrl:1
	global_load_dwordx4 v[116:119], v[150:151], off
	v_add_f32_dpp v174, v174, v174 row_ror:1 row_mask:0xf bank_mask:0xf bound_ctrl:1
	v_add_f32_dpp v176, v176, v176 row_ror:1 row_mask:0xf bank_mask:0xf bound_ctrl:1
	v_pk_fma_f32 v[68:69], v[174:175], v[32:33], v[56:57] op_sel_hi:[0,1,1] neg_lo:[1,0,0] neg_hi:[1,0,0]
	v_pk_fma_f32 v[70:71], v[174:175], v[34:35], v[58:59] op_sel_hi:[0,1,1] neg_lo:[1,0,0] neg_hi:[1,0,0]
	v_cndmask_b32_e64 v60, v60, v176, s[20:21]
	s_waitcnt lgkmcnt(0)
	ds_read_b128 v[28:31], v156 offset:15488
	ds_read_b128 v[36:39], v156 offset:15520
	ds_read_u16_d16_hi v48, v157 offset:15488
	ds_read_b128 v[44:47], v156 offset:15552
	ds_read_b128 v[32:35], v156 offset:15504
	v_pk_mul_f32 v[172:173], v[68:69], v[4:5]
	v_pk_mul_f32 v[178:179], v[68:69], v[40:41]
	v_pk_fma_f32 v[172:173], v[70:71], v[6:7], v[172:173]
	v_pk_fma_f32 v[178:179], v[70:71], v[42:43], v[178:179]
	v_add_f32_e32 v172, v172, v173
	v_add_f32_e32 v178, v178, v179
	v_pk_mul_f32 v[52:53], v[24:25], v[12:13] op_sel_hi:[0,1]
	ds_read_b128 v[40:43], v156 offset:15536
	v_add_f32_dpp v172, v172, v172 row_ror:8 row_mask:0xf bank_mask:0xf bound_ctrl:1
	v_pk_mul_f32 v[54:55], v[24:25], v[14:15] op_sel_hi:[0,1]
	v_add_f32_dpp v178, v178, v178 row_ror:8 row_mask:0xf bank_mask:0xf bound_ctrl:1
	v_pk_fma_f32 v[56:57], v[68:69], v[20:21], v[52:53]
	v_add_f32_dpp v172, v172, v172 row_ror:4 row_mask:0xf bank_mask:0xf bound_ctrl:1
	v_pk_fma_f32 v[58:59], v[70:71], v[22:23], v[54:55]
	v_add_f32_dpp v178, v178, v178 row_ror:4 row_mask:0xf bank_mask:0xf bound_ctrl:1
	v_lshl_add_u64 v[144:145], v[144:145], 0, v[152:153]
	v_add_f32_dpp v172, v172, v172 row_ror:2 row_mask:0xf bank_mask:0xf bound_ctrl:1
	v_lshl_add_u64 v[146:147], v[146:147], 0, v[152:153]
	v_add_f32_dpp v178, v178, v178 row_ror:2 row_mask:0xf bank_mask:0xf bound_ctrl:1
	v_lshl_add_u64 v[148:149], v[148:149], 0, v[62:63]
	v_add_f32_dpp v172, v172, v172 row_ror:1 row_mask:0xf bank_mask:0xf bound_ctrl:1
	v_add_f32_dpp v178, v178, v178 row_ror:1 row_mask:0xf bank_mask:0xf bound_ctrl:1
	v_pk_fma_f32 v[68:69], v[172:173], v[8:9], v[56:57] op_sel_hi:[0,1,1] neg_lo:[1,0,0] neg_hi:[1,0,0]
	v_pk_fma_f32 v[70:71], v[172:173], v[10:11], v[58:59] op_sel_hi:[0,1,1] neg_lo:[1,0,0] neg_hi:[1,0,0]
	v_cndmask_b32_e64 v60, v60, v178, s[22:23]
	s_waitcnt lgkmcnt(0)
	ds_read_b128 v[4:7], v156 offset:16896
	ds_read_b128 v[12:15], v156 offset:16928
	ds_read_u16_d16_hi v24, v157 offset:16896
	ds_read_b128 v[20:23], v156 offset:16960
	ds_read_b128 v[8:11], v156 offset:16912
	v_pk_mul_f32 v[174:175], v[68:69], v[28:29]
	v_pk_mul_f32 v[176:177], v[68:69], v[16:17]
	v_pk_fma_f32 v[174:175], v[70:71], v[30:31], v[174:175]
	v_pk_fma_f32 v[176:177], v[70:71], v[18:19], v[176:177]
	v_add_f32_e32 v174, v174, v175
	v_add_f32_e32 v176, v176, v177
	v_pk_mul_f32 v[52:53], v[48:49], v[36:37] op_sel_hi:[0,1]
	ds_read_b128 v[16:19], v156 offset:16944
	v_add_f32_dpp v174, v174, v174 row_ror:8 row_mask:0xf bank_mask:0xf bound_ctrl:1
	v_pk_mul_f32 v[54:55], v[48:49], v[38:39] op_sel_hi:[0,1]
	v_add_f32_dpp v176, v176, v176 row_ror:8 row_mask:0xf bank_mask:0xf bound_ctrl:1
	v_pk_fma_f32 v[56:57], v[68:69], v[44:45], v[52:53]
	v_add_f32_dpp v174, v174, v174 row_ror:4 row_mask:0xf bank_mask:0xf bound_ctrl:1
	v_pk_fma_f32 v[58:59], v[70:71], v[46:47], v[54:55]
	v_add_f32_dpp v176, v176, v176 row_ror:4 row_mask:0xf bank_mask:0xf bound_ctrl:1
	v_lshl_add_u64 v[150:151], v[150:151], 0, v[64:65]
	v_add_f32_dpp v174, v174, v174 row_ror:2 row_mask:0xf bank_mask:0xf bound_ctrl:1
	v_add_u32_e32 v158, s43, v162
	v_add_f32_dpp v176, v176, v176 row_ror:2 row_mask:0xf bank_mask:0xf bound_ctrl:1
	v_add_u32_e32 v159, s43, v163
	v_add_f32_dpp v174, v174, v174 row_ror:1 row_mask:0xf bank_mask:0xf bound_ctrl:1
	v_add_f32_dpp v176, v176, v176 row_ror:1 row_mask:0xf bank_mask:0xf bound_ctrl:1
	v_pk_fma_f32 v[68:69], v[174:175], v[32:33], v[56:57] op_sel_hi:[0,1,1] neg_lo:[1,0,0] neg_hi:[1,0,0]
	v_pk_fma_f32 v[70:71], v[174:175], v[34:35], v[58:59] op_sel_hi:[0,1,1] neg_lo:[1,0,0] neg_hi:[1,0,0]
	v_cndmask_b32_e64 v60, v60, v176, s[24:25]
	s_waitcnt lgkmcnt(0)
; DEVI void rw_chain_task(const Params& p, int l, int seq, int head, int quarter, char* smem) {
;     ...
;     for (int c = 0; c < nch; c += 4) {
;       lds_barrier();
;       RW_STORE(R1, B1);
;       RW_LOAD(R1, c + 5);
;       RW_COMPUTE(B0, c);
;       lds_barrier();
;       RW_STORE(R2, B0);
;       RW_LOAD(R2, c + 6);
;       RW_COMPUTE(B1, c + 1);
;       lds_barrier();
;       RW_STORE(R3, B1);
;       RW_LOAD(R3, c + 7);
;       RW_COMPUTE(B0, c + 2);
;       lds_barrier();
;       RW_STORE(R0, B0);
;       RW_LOAD(R0, c + 8);
;       RW_COMPUTE(B1, c + 3);
;     }
	ds_read_b128 v[28:31], v156 offset:18304
	ds_read_b128 v[36:39], v156 offset:18336
	ds_read_u16_d16_hi v48, v157 offset:18304
	ds_read_b128 v[44:47], v156 offset:18368
	ds_read_b128 v[32:35], v156 offset:18320
	v_pk_mul_f32 v[172:173], v[68:69], v[4:5]
	v_pk_mul_f32 v[178:179], v[68:69], v[40:41]
	v_pk_fma_f32 v[172:173], v[70:71], v[6:7], v[172:173]
	v_pk_fma_f32 v[178:179], v[70:71], v[42:43], v[178:179]
	v_add_f32_e32 v172, v172, v173
	v_add_f32_e32 v178, v178, v179
	v_pk_mul_f32 v[52:53], v[24:25], v[12:13] op_sel_hi:[0,1]
	ds_read_b128 v[40:43], v156 offset:18352
	v_add_f32_dpp v172, v172, v172 row_ror:8 row_mask:0xf bank_mask:0xf bound_ctrl:1
	v_pk_mul_f32 v[54:55], v[24:25], v[14:15] op_sel_hi:[0,1]
	v_add_f32_dpp v178, v178, v178 row_ror:8 row_mask:0xf bank_mask:0xf bound_ctrl:1
	v_pk_fma_f32 v[56:57], v[68:69], v[20:21], v[52:53]
	v_add_f32_dpp v172, v172, v172 row_ror:4 row_mask:0xf bank_mask:0xf bound_ctrl:1
	v_pk_fma_f32 v[58:59], v[70:71], v[22:23], v[54:55]
	v_add_f32_dpp v178, v178, v178 row_ror:4 row_mask:0xf bank_mask:0xf bound_ctrl:1
	v_add_f32_dpp v172, v172, v172 row_ror:2 row_mask:0xf bank_mask:0xf bound_ctrl:1
	s_nop 0
	v_add_f32_dpp v178, v178, v178 row_ror:2 row_mask:0xf bank_mask:0xf bound_ctrl:1
	v_add_f32_dpp v172, v172, v172 row_ror:1 row_mask:0xf bank_mask:0xf bound_ctrl:1
	s_nop 0
	v_add_f32_dpp v178, v178, v178 row_ror:1 row_mask:0xf bank_mask:0xf bound_ctrl:1
	v_pk_fma_f32 v[68:69], v[172:173], v[8:9], v[56:57] op_sel_hi:[0,1,1] neg_lo:[1,0,0] neg_hi:[1,0,0]
	v_pk_fma_f32 v[70:71], v[172:173], v[10:11], v[58:59] op_sel_hi:[0,1,1] neg_lo:[1,0,0] neg_hi:[1,0,0]
	v_cndmask_b32_e64 v60, v60, v178, s[26:27]
	s_waitcnt lgkmcnt(0)
	ds_read_b128 v[4:7], v156 offset:19712
	ds_read_b128 v[12:15], v156 offset:19744
	ds_read_u16_d16_hi v24, v157 offset:19712
	ds_read_b128 v[20:23], v156 offset:19776
	ds_read_b128 v[8:11], v156 offset:19728
	v_pk_mul_f32 v[174:175], v[68:69], v[28:29]
	v_pk_mul_f32 v[176:177], v[68:69], v[16:17]
	v_pk_fma_f32 v[174:175], v[70:71], v[30:31], v[174:175]
	v_pk_fma_f32 v[176:177], v[70:71], v[18:19], v[176:177]
	v_add_f32_e32 v174, v174, v175
	v_add_f32_e32 v176, v176, v177
	v_pk_mul_f32 v[52:53], v[48:49], v[36:37] op_sel_hi:[0,1]
	ds_read_b128 v[16:19], v156 offset:19760
	v_add_f32_dpp v174, v174, v174 row_ror:8 row_mask:0xf bank_mask:0xf bound_ctrl:1
	v_pk_mul_f32 v[54:55], v[48:49], v[38:39] op_sel_hi:[0,1]
	v_add_f32_dpp v176, v176, v176 row_ror:8 row_mask:0xf bank_mask:0xf bound_ctrl:1
	v_pk_fma_f32 v[56:57], v[68:69], v[44:45], v[52:53]
	v_add_f32_dpp v174, v174, v174 row_ror:4 row_mask:0xf bank_mask:0xf bound_ctrl:1
	v_pk_fma_f32 v[58:59], v[70:71], v[46:47], v[54:55]
	v_add_f32_dpp v176, v176, v176 row_ror:4 row_mask:0xf bank_mask:0xf bound_ctrl:1
	v_add_f32_dpp v174, v174, v174 row_ror:2 row_mask:0xf bank_mask:0xf bound_ctrl:1
	s_nop 0
	v_add_f32_dpp v176, v176, v176 row_ror:2 row_mask:0xf bank_mask:0xf bound_ctrl:1
	v_add_f32_dpp v174, v174, v174 row_ror:1 row_mask:0xf bank_mask:0xf bound_ctrl:1
	s_nop 0
	v_add_f32_dpp v176, v176, v176 row_ror:1 row_mask:0xf bank_mask:0xf bound_ctrl:1
	v_pk_fma_f32 v[68:69], v[174:175], v[32:33], v[56:57] op_sel_hi:[0,1,1] neg_lo:[1,0,0] neg_hi:[1,0,0]
	v_pk_fma_f32 v[70:71], v[174:175], v[34:35], v[58:59] op_sel_hi:[0,1,1] neg_lo:[1,0,0] neg_hi:[1,0,0]
	v_cndmask_b32_e64 v60, v60, v176, s[28:29]
	s_waitcnt lgkmcnt(0)
	ds_read_b128 v[28:31], v156 offset:21120
	ds_read_b128 v[36:39], v156 offset:21152
	ds_read_u16_d16_hi v48, v157 offset:21120
	ds_read_b128 v[44:47], v156 offset:21184
	ds_read_b128 v[32:35], v156 offset:21136
	v_pk_mul_f32 v[172:173], v[68:69], v[4:5]
	v_pk_mul_f32 v[178:179], v[68:69], v[40:41]
	v_pk_fma_f32 v[172:173], v[70:71], v[6:7], v[172:173]
	v_pk_fma_f32 v[178:179], v[70:71], v[42:43], v[178:179]
	v_add_f32_e32 v172, v172, v173
	v_add_f32_e32 v178, v178, v179
	v_pk_mul_f32 v[52:53], v[24:25], v[12:13] op_sel_hi:[0,1]
	ds_read_b128 v[40:43], v156 offset:21168
	v_add_f32_dpp v172, v172, v172 row_ror:8 row_mask:0xf bank_mask:0xf bound_ctrl:1
	v_pk_mul_f32 v[54:55], v[24:25], v[14:15] op_sel_hi:[0,1]
	v_add_f32_dpp v178, v178, v178 row_ror:8 row_mask:0xf bank_mask:0xf bound_ctrl:1
	v_pk_fma_f32 v[56:57], v[68:69], v[20:21], v[52:53]
	v_add_f32_dpp v172, v172, v172 row_ror:4 row_mask:0xf bank_mask:0xf bound_ctrl:1
	v_pk_fma_f32 v[58:59], v[70:71], v[22:23], v[54:55]
	v_add_f32_dpp v178, v178, v178 row_ror:4 row_mask:0xf bank_mask:0xf bound_ctrl:1
	v_add_f32_dpp v172, v172, v172 row_ror:2 row_mask:0xf bank_mask:0xf bound_ctrl:1
	s_nop 0
	v_add_f32_dpp v178, v178, v178 row_ror:2 row_mask:0xf bank_mask:0xf bound_ctrl:1
	v_add_f32_dpp v172, v172, v172 row_ror:1 row_mask:0xf bank_mask:0xf bound_ctrl:1
	s_nop 0
	v_add_f32_dpp v178, v178, v178 row_ror:1 row_mask:0xf bank_mask:0xf bound_ctrl:1
	v_pk_fma_f32 v[68:69], v[172:173], v[8:9], v[56:57] op_sel_hi:[0,1,1] neg_lo:[1,0,0] neg_hi:[1,0,0]
	v_pk_fma_f32 v[70:71], v[172:173], v[10:11], v[58:59] op_sel_hi:[0,1,1] neg_lo:[1,0,0] neg_hi:[1,0,0]
	v_cndmask_b32_e64 v60, v60, v178, s[30:31]
	s_waitcnt lgkmcnt(0)
	ds_read_b128 v[4:7], v158 offset:0
	ds_read_b128 v[12:15], v158 offset:32
	ds_read_u16_d16_hi v24, v159 offset:0
	ds_read_b128 v[20:23], v158 offset:64
	ds_read_b128 v[8:11], v158 offset:16
	v_pk_mul_f32 v[174:175], v[68:69], v[28:29]
	v_pk_mul_f32 v[176:177], v[68:69], v[16:17]
	v_pk_fma_f32 v[174:175], v[70:71], v[30:31], v[174:175]
	v_pk_fma_f32 v[176:177], v[70:71], v[18:19], v[176:177]
	v_add_f32_e32 v174, v174, v175
	v_add_f32_e32 v176, v176, v177
	v_pk_mul_f32 v[52:53], v[48:49], v[36:37] op_sel_hi:[0,1]
	ds_read_b128 v[16:19], v158 offset:48
	v_add_f32_dpp v174, v174, v174 row_ror:8 row_mask:0xf bank_mask:0xf bound_ctrl:1
	v_pk_mul_f32 v[54:55], v[48:49], v[38:39] op_sel_hi:[0,1]
	v_add_f32_dpp v176, v176, v176 row_ror:8 row_mask:0xf bank_mask:0xf bound_ctrl:1
	v_pk_fma_f32 v[56:57], v[68:69], v[44:45], v[52:53]
	v_add_f32_dpp v174, v174, v174 row_ror:4 row_mask:0xf bank_mask:0xf bound_ctrl:1
	v_pk_fma_f32 v[58:59], v[70:71], v[46:47], v[54:55]
	v_add_f32_dpp v176, v176, v176 row_ror:4 row_mask:0xf bank_mask:0xf bound_ctrl:1
	v_add_f32_dpp v174, v174, v174 row_ror:2 row_mask:0xf bank_mask:0xf bound_ctrl:1
	s_nop 0
	v_add_f32_dpp v176, v176, v176 row_ror:2 row_mask:0xf bank_mask:0xf bound_ctrl:1
	v_add_f32_dpp v174, v174, v174 row_ror:1 row_mask:0xf bank_mask:0xf bound_ctrl:1
	s_nop 0
	v_add_f32_dpp v176, v176, v176 row_ror:1 row_mask:0xf bank_mask:0xf bound_ctrl:1
	v_pk_fma_f32 v[68:69], v[174:175], v[32:33], v[56:57] op_sel_hi:[0,1,1] neg_lo:[1,0,0] neg_hi:[1,0,0]
	v_pk_fma_f32 v[70:71], v[174:175], v[34:35], v[58:59] op_sel_hi:[0,1,1] neg_lo:[1,0,0] neg_hi:[1,0,0]
	v_cndmask_b32_e64 v60, v60, v176, s[34:35]
	s_waitcnt lgkmcnt(0)
	s_barrier
	s_mov_b32 vcc_lo, s42
	s_mov_b32 s42, s43
	s_mov_b32 s43, s45
	s_mov_b32 s45, vcc_lo
	v_add_u32_e32 v156, s42, v162
	v_add_u32_e32 v157, s42, v163
	v_add_u32_e32 v155, s45, v164
	v_add_u32_e32 v165, s45, v167
	v_add_u32_e32 v166, s45, v168
	s_waitcnt lgkmcnt(0)
	ds_read_b128 v[28:31], v156 offset:1408
	ds_read_b128 v[36:39], v156 offset:1440
	ds_read_u16_d16_hi v48, v157 offset:1408
	ds_read_b128 v[44:47], v156 offset:1472
	ds_read_b128 v[32:35], v156 offset:1424
	v_pk_mul_f32 v[172:173], v[68:69], v[4:5]
	v_pk_mul_f32 v[178:179], v[68:69], v[40:41]
	v_pk_fma_f32 v[172:173], v[70:71], v[6:7], v[172:173]
	v_pk_fma_f32 v[178:179], v[70:71], v[42:43], v[178:179]
	v_add_f32_e32 v172, v172, v173
	v_add_f32_e32 v178, v178, v179
	v_pk_mul_f32 v[52:53], v[24:25], v[12:13] op_sel_hi:[0,1]
	ds_read_b128 v[40:43], v156 offset:1456
	v_add_f32_dpp v172, v172, v172 row_ror:8 row_mask:0xf bank_mask:0xf bound_ctrl:1
	v_pk_mul_f32 v[54:55], v[24:25], v[14:15] op_sel_hi:[0,1]
	v_add_f32_dpp v178, v178, v178 row_ror:8 row_mask:0xf bank_mask:0xf bound_ctrl:1
	v_pk_fma_f32 v[56:57], v[68:69], v[20:21], v[52:53]
	v_add_f32_dpp v172, v172, v172 row_ror:4 row_mask:0xf bank_mask:0xf bound_ctrl:1
	v_pk_fma_f32 v[58:59], v[70:71], v[22:23], v[54:55]
	v_add_f32_dpp v178, v178, v178 row_ror:4 row_mask:0xf bank_mask:0xf bound_ctrl:1
	v_add_f32_dpp v172, v172, v172 row_ror:2 row_mask:0xf bank_mask:0xf bound_ctrl:1
	s_nop 0
	v_add_f32_dpp v178, v178, v178 row_ror:2 row_mask:0xf bank_mask:0xf bound_ctrl:1
	v_add_f32_dpp v172, v172, v172 row_ror:1 row_mask:0xf bank_mask:0xf bound_ctrl:1
	s_nop 0
	v_add_f32_dpp v178, v178, v178 row_ror:1 row_mask:0xf bank_mask:0xf bound_ctrl:1
	v_pk_fma_f32 v[68:69], v[172:173], v[8:9], v[56:57] op_sel_hi:[0,1,1] neg_lo:[1,0,0] neg_hi:[1,0,0]
	v_pk_fma_f32 v[70:71], v[172:173], v[10:11], v[58:59] op_sel_hi:[0,1,1] neg_lo:[1,0,0] neg_hi:[1,0,0]
	v_cndmask_b32_e64 v60, v60, v178, s[36:37]
	v_bfe_u32 v61, v60, 16, 1
	v_add3_u32 v61, v60, v61, s33
	global_store_short_d16_hi v[160:161], v61, off
	v_lshl_add_u64 v[160:161], v[160:161], 0, s[46:47]
	s_waitcnt lgkmcnt(0)
	ds_read_b128 v[4:7], v156 offset:2816
	ds_read_b128 v[12:15], v156 offset:2848
	ds_read_u16_d16_hi v24, v157 offset:2816
	ds_read_b128 v[20:23], v156 offset:2880
	ds_read_b128 v[8:11], v156 offset:2832
	v_pk_mul_f32 v[174:175], v[68:69], v[28:29]
	v_pk_mul_f32 v[176:177], v[68:69], v[16:17]
	v_pk_fma_f32 v[174:175], v[70:71], v[30:31], v[174:175]
	v_pk_fma_f32 v[176:177], v[70:71], v[18:19], v[176:177]
	v_add_f32_e32 v174, v174, v175
	v_add_f32_e32 v176, v176, v177
	v_pk_mul_f32 v[52:53], v[48:49], v[36:37] op_sel_hi:[0,1]
	ds_read_b128 v[16:19], v156 offset:2864
	v_add_f32_dpp v174, v174, v174 row_ror:8 row_mask:0xf bank_mask:0xf bound_ctrl:1
	v_pk_mul_f32 v[54:55], v[48:49], v[38:39] op_sel_hi:[0,1]
	v_add_f32_dpp v176, v176, v176 row_ror:8 row_mask:0xf bank_mask:0xf bound_ctrl:1
	v_pk_fma_f32 v[56:57], v[68:69], v[44:45], v[52:53]
	v_add_f32_dpp v174, v174, v174 row_ror:4 row_mask:0xf bank_mask:0xf bound_ctrl:1
	v_pk_fma_f32 v[58:59], v[70:71], v[46:47], v[54:55]
	v_add_f32_dpp v176, v176, v176 row_ror:4 row_mask:0xf bank_mask:0xf bound_ctrl:1
	s_waitcnt vmcnt(12)
	v_add_f32_dpp v174, v174, v174 row_ror:2 row_mask:0xf bank_mask:0xf bound_ctrl:1
	v_lshlrev_b32_e32 v136, 16, v120
	v_add_f32_dpp v176, v176, v176 row_ror:2 row_mask:0xf bank_mask:0xf bound_ctrl:1
	v_and_b32_e32 v137, 0xffff0000, v120
	v_add_f32_dpp v174, v174, v174 row_ror:1 row_mask:0xf bank_mask:0xf bound_ctrl:1
	v_add_f32_dpp v176, v176, v176 row_ror:1 row_mask:0xf bank_mask:0xf bound_ctrl:1
	v_pk_fma_f32 v[68:69], v[174:175], v[32:33], v[56:57] op_sel_hi:[0,1,1] neg_lo:[1,0,0] neg_hi:[1,0,0]
	v_pk_fma_f32 v[70:71], v[174:175], v[34:35], v[58:59] op_sel_hi:[0,1,1] neg_lo:[1,0,0] neg_hi:[1,0,0]
	v_cndmask_b32_e64 v60, v60, v176, s[4:5]
	s_waitcnt lgkmcnt(0)
	ds_read_b128 v[28:31], v156 offset:4224
	ds_read_b128 v[36:39], v156 offset:4256
	ds_read_u16_d16_hi v48, v157 offset:4224
	ds_read_b128 v[44:47], v156 offset:4288
	ds_read_b128 v[32:35], v156 offset:4240
	v_pk_mul_f32 v[172:173], v[68:69], v[4:5]
	v_pk_mul_f32 v[178:179], v[68:69], v[40:41]
	v_pk_fma_f32 v[172:173], v[70:71], v[6:7], v[172:173]
	v_pk_fma_f32 v[178:179], v[70:71], v[42:43], v[178:179]
	v_add_f32_e32 v172, v172, v173
	v_add_f32_e32 v178, v178, v179
	v_pk_mul_f32 v[52:53], v[24:25], v[12:13] op_sel_hi:[0,1]
	ds_read_b128 v[40:43], v156 offset:4272
	v_add_f32_dpp v172, v172, v172 row_ror:8 row_mask:0xf bank_mask:0xf bound_ctrl:1
	v_pk_mul_f32 v[54:55], v[24:25], v[14:15] op_sel_hi:[0,1]
	v_add_f32_dpp v178, v178, v178 row_ror:8 row_mask:0xf bank_mask:0xf bound_ctrl:1
	v_pk_fma_f32 v[56:57], v[68:69], v[20:21], v[52:53]
	v_add_f32_dpp v172, v172, v172 row_ror:4 row_mask:0xf bank_mask:0xf bound_ctrl:1
	v_pk_fma_f32 v[58:59], v[70:71], v[22:23], v[54:55]
	v_add_f32_dpp v178, v178, v178 row_ror:4 row_mask:0xf bank_mask:0xf bound_ctrl:1
	v_lshlrev_b32_e32 v138, 16, v121
	v_add_f32_dpp v172, v172, v172 row_ror:2 row_mask:0xf bank_mask:0xf bound_ctrl:1
	v_and_b32_e32 v139, 0xffff0000, v121
	v_add_f32_dpp v178, v178, v178 row_ror:2 row_mask:0xf bank_mask:0xf bound_ctrl:1
	v_lshlrev_b32_e32 v140, 16, v122
	v_add_f32_dpp v172, v172, v172 row_ror:1 row_mask:0xf bank_mask:0xf bound_ctrl:1
	v_add_f32_dpp v178, v178, v178 row_ror:1 row_mask:0xf bank_mask:0xf bound_ctrl:1
	v_pk_fma_f32 v[68:69], v[172:173], v[8:9], v[56:57] op_sel_hi:[0,1,1] neg_lo:[1,0,0] neg_hi:[1,0,0]
	v_pk_fma_f32 v[70:71], v[172:173], v[10:11], v[58:59] op_sel_hi:[0,1,1] neg_lo:[1,0,0] neg_hi:[1,0,0]
	v_cndmask_b32_e64 v60, v60, v178, s[6:7]
	s_waitcnt lgkmcnt(0)
	ds_read_b128 v[4:7], v156 offset:5632
	ds_read_b128 v[12:15], v156 offset:5664
	ds_read_u16_d16_hi v24, v157 offset:5632
	ds_read_b128 v[20:23], v156 offset:5696
	ds_read_b128 v[8:11], v156 offset:5648
	v_pk_mul_f32 v[174:175], v[68:69], v[28:29]
	v_pk_mul_f32 v[176:177], v[68:69], v[16:17]
	v_pk_fma_f32 v[174:175], v[70:71], v[30:31], v[174:175]
	v_pk_fma_f32 v[176:177], v[70:71], v[18:19], v[176:177]
	v_add_f32_e32 v174, v174, v175
	v_add_f32_e32 v176, v176, v177
	v_pk_mul_f32 v[52:53], v[48:49], v[36:37] op_sel_hi:[0,1]
	ds_read_b128 v[16:19], v156 offset:5680
	v_add_f32_dpp v174, v174, v174 row_ror:8 row_mask:0xf bank_mask:0xf bound_ctrl:1
	v_pk_mul_f32 v[54:55], v[48:49], v[38:39] op_sel_hi:[0,1]
	v_add_f32_dpp v176, v176, v176 row_ror:8 row_mask:0xf bank_mask:0xf bound_ctrl:1
	v_pk_fma_f32 v[56:57], v[68:69], v[44:45], v[52:53]
	v_add_f32_dpp v174, v174, v174 row_ror:4 row_mask:0xf bank_mask:0xf bound_ctrl:1
	v_pk_fma_f32 v[58:59], v[70:71], v[46:47], v[54:55]
	v_add_f32_dpp v176, v176, v176 row_ror:4 row_mask:0xf bank_mask:0xf bound_ctrl:1
	v_and_b32_e32 v141, 0xffff0000, v122
	v_add_f32_dpp v174, v174, v174 row_ror:2 row_mask:0xf bank_mask:0xf bound_ctrl:1
	v_lshlrev_b32_e32 v142, 16, v123
	v_add_f32_dpp v176, v176, v176 row_ror:2 row_mask:0xf bank_mask:0xf bound_ctrl:1
	v_and_b32_e32 v143, 0xffff0000, v123
	v_add_f32_dpp v174, v174, v174 row_ror:1 row_mask:0xf bank_mask:0xf bound_ctrl:1
	v_add_f32_dpp v176, v176, v176 row_ror:1 row_mask:0xf bank_mask:0xf bound_ctrl:1
	v_pk_fma_f32 v[68:69], v[174:175], v[32:33], v[56:57] op_sel_hi:[0,1,1] neg_lo:[1,0,0] neg_hi:[1,0,0]
	v_pk_fma_f32 v[70:71], v[174:175], v[34:35], v[58:59] op_sel_hi:[0,1,1] neg_lo:[1,0,0] neg_hi:[1,0,0]
	v_cndmask_b32_e64 v60, v60, v176, s[8:9]
	s_waitcnt lgkmcnt(0)
	ds_read_b128 v[28:31], v156 offset:7040
	ds_read_b128 v[36:39], v156 offset:7072
	ds_read_u16_d16_hi v48, v157 offset:7040
	ds_read_b128 v[44:47], v156 offset:7104
	ds_read_b128 v[32:35], v156 offset:7056
	v_pk_mul_f32 v[172:173], v[68:69], v[4:5]
	v_pk_mul_f32 v[178:179], v[68:69], v[40:41]
	v_pk_fma_f32 v[172:173], v[70:71], v[6:7], v[172:173]
	v_pk_fma_f32 v[178:179], v[70:71], v[42:43], v[178:179]
	v_add_f32_e32 v172, v172, v173
	v_add_f32_e32 v178, v178, v179
	v_pk_mul_f32 v[52:53], v[24:25], v[12:13] op_sel_hi:[0,1]
	ds_read_b128 v[40:43], v156 offset:7088
	v_add_f32_dpp v172, v172, v172 row_ror:8 row_mask:0xf bank_mask:0xf bound_ctrl:1
	v_pk_mul_f32 v[54:55], v[24:25], v[14:15] op_sel_hi:[0,1]
	v_add_f32_dpp v178, v178, v178 row_ror:8 row_mask:0xf bank_mask:0xf bound_ctrl:1
	v_pk_fma_f32 v[56:57], v[68:69], v[20:21], v[52:53]
	v_add_f32_dpp v172, v172, v172 row_ror:4 row_mask:0xf bank_mask:0xf bound_ctrl:1
	v_pk_fma_f32 v[58:59], v[70:71], v[22:23], v[54:55]
	v_add_f32_dpp v178, v178, v178 row_ror:4 row_mask:0xf bank_mask:0xf bound_ctrl:1
	ds_write_b128 v155, v[136:139] offset:0
	v_add_f32_dpp v172, v172, v172 row_ror:2 row_mask:0xf bank_mask:0xf bound_ctrl:1
	ds_write_b128 v155, v[140:143] offset:80
	v_add_f32_dpp v178, v178, v178 row_ror:2 row_mask:0xf bank_mask:0xf bound_ctrl:1
	v_lshlrev_b32_e32 v136, 16, v124
	v_add_f32_dpp v172, v172, v172 row_ror:1 row_mask:0xf bank_mask:0xf bound_ctrl:1
	v_add_f32_dpp v178, v178, v178 row_ror:1 row_mask:0xf bank_mask:0xf bound_ctrl:1
	v_pk_fma_f32 v[68:69], v[172:173], v[8:9], v[56:57] op_sel_hi:[0,1,1] neg_lo:[1,0,0] neg_hi:[1,0,0]
	v_pk_fma_f32 v[70:71], v[172:173], v[10:11], v[58:59] op_sel_hi:[0,1,1] neg_lo:[1,0,0] neg_hi:[1,0,0]
	v_cndmask_b32_e64 v60, v60, v178, s[10:11]
	s_waitcnt lgkmcnt(2)
	ds_read_b128 v[4:7], v156 offset:8448
	ds_read_b128 v[12:15], v156 offset:8480
	ds_read_u16_d16_hi v24, v157 offset:8448
	ds_read_b128 v[20:23], v156 offset:8512
	ds_read_b128 v[8:11], v156 offset:8464
	v_pk_mul_f32 v[174:175], v[68:69], v[28:29]
	v_pk_mul_f32 v[176:177], v[68:69], v[16:17]
	v_pk_fma_f32 v[174:175], v[70:71], v[30:31], v[174:175]
	v_pk_fma_f32 v[176:177], v[70:71], v[18:19], v[176:177]
	v_add_f32_e32 v174, v174, v175
	v_add_f32_e32 v176, v176, v177
	v_pk_mul_f32 v[52:53], v[48:49], v[36:37] op_sel_hi:[0,1]
	ds_read_b128 v[16:19], v156 offset:8496
	v_add_f32_dpp v174, v174, v174 row_ror:8 row_mask:0xf bank_mask:0xf bound_ctrl:1
	v_pk_mul_f32 v[54:55], v[48:49], v[38:39] op_sel_hi:[0,1]
	v_add_f32_dpp v176, v176, v176 row_ror:8 row_mask:0xf bank_mask:0xf bound_ctrl:1
	v_pk_fma_f32 v[56:57], v[68:69], v[44:45], v[52:53]
	v_add_f32_dpp v174, v174, v174 row_ror:4 row_mask:0xf bank_mask:0xf bound_ctrl:1
	v_pk_fma_f32 v[58:59], v[70:71], v[46:47], v[54:55]
	v_add_f32_dpp v176, v176, v176 row_ror:4 row_mask:0xf bank_mask:0xf bound_ctrl:1
	v_and_b32_e32 v137, 0xffff0000, v124
	v_add_f32_dpp v174, v174, v174 row_ror:2 row_mask:0xf bank_mask:0xf bound_ctrl:1
	v_lshlrev_b32_e32 v138, 16, v125
	v_add_f32_dpp v176, v176, v176 row_ror:2 row_mask:0xf bank_mask:0xf bound_ctrl:1
	v_and_b32_e32 v139, 0xffff0000, v125
	v_add_f32_dpp v174, v174, v174 row_ror:1 row_mask:0xf bank_mask:0xf bound_ctrl:1
	v_add_f32_dpp v176, v176, v176 row_ror:1 row_mask:0xf bank_mask:0xf bound_ctrl:1
	v_pk_fma_f32 v[68:69], v[174:175], v[32:33], v[56:57] op_sel_hi:[0,1,1] neg_lo:[1,0,0] neg_hi:[1,0,0]
	v_pk_fma_f32 v[70:71], v[174:175], v[34:35], v[58:59] op_sel_hi:[0,1,1] neg_lo:[1,0,0] neg_hi:[1,0,0]
	v_cndmask_b32_e64 v60, v60, v176, s[12:13]
	s_waitcnt lgkmcnt(0)
	ds_read_b128 v[28:31], v156 offset:9856
	ds_read_b128 v[36:39], v156 offset:9888
	ds_read_u16_d16_hi v48, v157 offset:9856
	ds_read_b128 v[44:47], v156 offset:9920
	ds_read_b128 v[32:35], v156 offset:9872
	v_pk_mul_f32 v[172:173], v[68:69], v[4:5]
	v_pk_mul_f32 v[178:179], v[68:69], v[40:41]
	v_pk_fma_f32 v[172:173], v[70:71], v[6:7], v[172:173]
	v_pk_fma_f32 v[178:179], v[70:71], v[42:43], v[178:179]
	v_add_f32_e32 v172, v172, v173
	v_add_f32_e32 v178, v178, v179
	v_pk_mul_f32 v[52:53], v[24:25], v[12:13] op_sel_hi:[0,1]
	ds_read_b128 v[40:43], v156 offset:9904
	v_add_f32_dpp v172, v172, v172 row_ror:8 row_mask:0xf bank_mask:0xf bound_ctrl:1
	v_pk_mul_f32 v[54:55], v[24:25], v[14:15] op_sel_hi:[0,1]
	v_add_f32_dpp v178, v178, v178 row_ror:8 row_mask:0xf bank_mask:0xf bound_ctrl:1
	v_pk_fma_f32 v[56:57], v[68:69], v[20:21], v[52:53]
	v_add_f32_dpp v172, v172, v172 row_ror:4 row_mask:0xf bank_mask:0xf bound_ctrl:1
	v_pk_fma_f32 v[58:59], v[70:71], v[22:23], v[54:55]
	v_add_f32_dpp v178, v178, v178 row_ror:4 row_mask:0xf bank_mask:0xf bound_ctrl:1
	v_lshlrev_b32_e32 v140, 16, v126
	v_add_f32_dpp v172, v172, v172 row_ror:2 row_mask:0xf bank_mask:0xf bound_ctrl:1
	v_and_b32_e32 v141, 0xffff0000, v126
	v_add_f32_dpp v178, v178, v178 row_ror:2 row_mask:0xf bank_mask:0xf bound_ctrl:1
	v_lshlrev_b32_e32 v142, 16, v127
	v_add_f32_dpp v172, v172, v172 row_ror:1 row_mask:0xf bank_mask:0xf bound_ctrl:1
	v_add_f32_dpp v178, v178, v178 row_ror:1 row_mask:0xf bank_mask:0xf bound_ctrl:1
	v_pk_fma_f32 v[68:69], v[172:173], v[8:9], v[56:57] op_sel_hi:[0,1,1] neg_lo:[1,0,0] neg_hi:[1,0,0]
	v_pk_fma_f32 v[70:71], v[172:173], v[10:11], v[58:59] op_sel_hi:[0,1,1] neg_lo:[1,0,0] neg_hi:[1,0,0]
	v_cndmask_b32_e64 v60, v60, v178, s[14:15]
	s_waitcnt lgkmcnt(0)
	ds_read_b128 v[4:7], v156 offset:11264
	ds_read_b128 v[12:15], v156 offset:11296
	ds_read_u16_d16_hi v24, v157 offset:11264
	ds_read_b128 v[20:23], v156 offset:11328
	ds_read_b128 v[8:11], v156 offset:11280
	v_pk_mul_f32 v[174:175], v[68:69], v[28:29]
	v_pk_mul_f32 v[176:177], v[68:69], v[16:17]
	v_pk_fma_f32 v[174:175], v[70:71], v[30:31], v[174:175]
	v_pk_fma_f32 v[176:177], v[70:71], v[18:19], v[176:177]
	v_add_f32_e32 v174, v174, v175
	v_add_f32_e32 v176, v176, v177
	v_pk_mul_f32 v[52:53], v[48:49], v[36:37] op_sel_hi:[0,1]
	ds_read_b128 v[16:19], v156 offset:11312
	v_add_f32_dpp v174, v174, v174 row_ror:8 row_mask:0xf bank_mask:0xf bound_ctrl:1
	v_pk_mul_f32 v[54:55], v[48:49], v[38:39] op_sel_hi:[0,1]
	v_add_f32_dpp v176, v176, v176 row_ror:8 row_mask:0xf bank_mask:0xf bound_ctrl:1
	v_pk_fma_f32 v[56:57], v[68:69], v[44:45], v[52:53]
	v_add_f32_dpp v174, v174, v174 row_ror:4 row_mask:0xf bank_mask:0xf bound_ctrl:1
	v_pk_fma_f32 v[58:59], v[70:71], v[46:47], v[54:55]
	v_add_f32_dpp v176, v176, v176 row_ror:4 row_mask:0xf bank_mask:0xf bound_ctrl:1
	v_and_b32_e32 v143, 0xffff0000, v127
	v_add_f32_dpp v174, v174, v174 row_ror:2 row_mask:0xf bank_mask:0xf bound_ctrl:1
	ds_write_b128 v155, v[136:139] offset:11264
	v_add_f32_dpp v176, v176, v176 row_ror:2 row_mask:0xf bank_mask:0xf bound_ctrl:1
	ds_write_b128 v155, v[140:143] offset:11344
	v_add_f32_dpp v174, v174, v174 row_ror:1 row_mask:0xf bank_mask:0xf bound_ctrl:1
	v_add_f32_dpp v176, v176, v176 row_ror:1 row_mask:0xf bank_mask:0xf bound_ctrl:1
	v_pk_fma_f32 v[68:69], v[174:175], v[32:33], v[56:57] op_sel_hi:[0,1,1] neg_lo:[1,0,0] neg_hi:[1,0,0]
	v_pk_fma_f32 v[70:71], v[174:175], v[34:35], v[58:59] op_sel_hi:[0,1,1] neg_lo:[1,0,0] neg_hi:[1,0,0]
	v_cndmask_b32_e64 v60, v60, v176, s[16:17]
	s_waitcnt lgkmcnt(2)
	ds_read_b128 v[28:31], v156 offset:12672
	ds_read_b128 v[36:39], v156 offset:12704
	ds_read_u16_d16_hi v48, v157 offset:12672
	ds_read_b128 v[44:47], v156 offset:12736
	ds_read_b128 v[32:35], v156 offset:12688
	v_pk_mul_f32 v[172:173], v[68:69], v[4:5]
	v_pk_mul_f32 v[178:179], v[68:69], v[40:41]
	v_pk_fma_f32 v[172:173], v[70:71], v[6:7], v[172:173]
	v_pk_fma_f32 v[178:179], v[70:71], v[42:43], v[178:179]
	v_add_f32_e32 v172, v172, v173
	v_add_f32_e32 v178, v178, v179
	v_pk_mul_f32 v[52:53], v[24:25], v[12:13] op_sel_hi:[0,1]
	ds_read_b128 v[40:43], v156 offset:12720
	v_add_f32_dpp v172, v172, v172 row_ror:8 row_mask:0xf bank_mask:0xf bound_ctrl:1
	v_pk_mul_f32 v[54:55], v[24:25], v[14:15] op_sel_hi:[0,1]
	v_add_f32_dpp v178, v178, v178 row_ror:8 row_mask:0xf bank_mask:0xf bound_ctrl:1
	v_pk_fma_f32 v[56:57], v[68:69], v[20:21], v[52:53]
	v_add_f32_dpp v172, v172, v172 row_ror:4 row_mask:0xf bank_mask:0xf bound_ctrl:1
	v_pk_fma_f32 v[58:59], v[70:71], v[22:23], v[54:55]
	v_add_f32_dpp v178, v178, v178 row_ror:4 row_mask:0xf bank_mask:0xf bound_ctrl:1
	ds_write_b128 v165, v[128:131]
	v_add_f32_dpp v172, v172, v172 row_ror:2 row_mask:0xf bank_mask:0xf bound_ctrl:1
	ds_write_b128 v166, v[132:135]
	v_add_f32_dpp v178, v178, v178 row_ror:2 row_mask:0xf bank_mask:0xf bound_ctrl:1
	global_load_dwordx4 v[120:123], v[144:145], off
	v_add_f32_dpp v172, v172, v172 row_ror:1 row_mask:0xf bank_mask:0xf bound_ctrl:1
	v_add_f32_dpp v178, v178, v178 row_ror:1 row_mask:0xf bank_mask:0xf bound_ctrl:1
	v_pk_fma_f32 v[68:69], v[172:173], v[8:9], v[56:57] op_sel_hi:[0,1,1] neg_lo:[1,0,0] neg_hi:[1,0,0]
	v_pk_fma_f32 v[70:71], v[172:173], v[10:11], v[58:59] op_sel_hi:[0,1,1] neg_lo:[1,0,0] neg_hi:[1,0,0]
	v_cndmask_b32_e64 v60, v60, v178, s[18:19]
	s_waitcnt lgkmcnt(2)
	ds_read_b128 v[4:7], v156 offset:14080
	ds_read_b128 v[12:15], v156 offset:14112
	ds_read_u16_d16_hi v24, v157 offset:14080
	ds_read_b128 v[20:23], v156 offset:14144
	ds_read_b128 v[8:11], v156 offset:14096
	v_pk_mul_f32 v[174:175], v[68:69], v[28:29]
	v_pk_mul_f32 v[176:177], v[68:69], v[16:17]
	v_pk_fma_f32 v[174:175], v[70:71], v[30:31], v[174:175]
	v_pk_fma_f32 v[176:177], v[70:71], v[18:19], v[176:177]
	v_add_f32_e32 v174, v174, v175
	v_add_f32_e32 v176, v176, v177
	v_pk_mul_f32 v[52:53], v[48:49], v[36:37] op_sel_hi:[0,1]
	ds_read_b128 v[16:19], v156 offset:14128
	v_add_f32_dpp v174, v174, v174 row_ror:8 row_mask:0xf bank_mask:0xf bound_ctrl:1
	v_pk_mul_f32 v[54:55], v[48:49], v[38:39] op_sel_hi:[0,1]
	v_add_f32_dpp v176, v176, v176 row_ror:8 row_mask:0xf bank_mask:0xf bound_ctrl:1
	v_pk_fma_f32 v[56:57], v[68:69], v[44:45], v[52:53]
	v_add_f32_dpp v174, v174, v174 row_ror:4 row_mask:0xf bank_mask:0xf bound_ctrl:1
	v_pk_fma_f32 v[58:59], v[70:71], v[46:47], v[54:55]
	v_add_f32_dpp v176, v176, v176 row_ror:4 row_mask:0xf bank_mask:0xf bound_ctrl:1
	global_load_dwordx4 v[124:127], v[146:147], off
	v_add_f32_dpp v174, v174, v174 row_ror:2 row_mask:0xf bank_mask:0xf bound_ctrl:1
	global_load_dwordx4 v[128:131], v[148:149], off
	v_add_f32_dpp v176, v176, v176 row_ror:2 row_mask:0xf bank_mask:0xf bound_ctrl:1
	global_load_dwordx4 v[132:135], v[150:151], off
	v_add_f32_dpp v174, v174, v174 row_ror:1 row_mask:0xf bank_mask:0xf bound_ctrl:1
	v_add_f32_dpp v176, v176, v176 row_ror:1 row_mask:0xf bank_mask:0xf bound_ctrl:1
	v_pk_fma_f32 v[68:69], v[174:175], v[32:33], v[56:57] op_sel_hi:[0,1,1] neg_lo:[1,0,0] neg_hi:[1,0,0]
	v_pk_fma_f32 v[70:71], v[174:175], v[34:35], v[58:59] op_sel_hi:[0,1,1] neg_lo:[1,0,0] neg_hi:[1,0,0]
	v_cndmask_b32_e64 v60, v60, v176, s[20:21]
	s_waitcnt lgkmcnt(0)
	ds_read_b128 v[28:31], v156 offset:15488
	ds_read_b128 v[36:39], v156 offset:15520
	ds_read_u16_d16_hi v48, v157 offset:15488
	ds_read_b128 v[44:47], v156 offset:15552
	ds_read_b128 v[32:35], v156 offset:15504
	v_pk_mul_f32 v[172:173], v[68:69], v[4:5]
	v_pk_mul_f32 v[178:179], v[68:69], v[40:41]
	v_pk_fma_f32 v[172:173], v[70:71], v[6:7], v[172:173]
	v_pk_fma_f32 v[178:179], v[70:71], v[42:43], v[178:179]
	v_add_f32_e32 v172, v172, v173
	v_add_f32_e32 v178, v178, v179
	v_pk_mul_f32 v[52:53], v[24:25], v[12:13] op_sel_hi:[0,1]
	ds_read_b128 v[40:43], v156 offset:15536
	v_add_f32_dpp v172, v172, v172 row_ror:8 row_mask:0xf bank_mask:0xf bound_ctrl:1
	v_pk_mul_f32 v[54:55], v[24:25], v[14:15] op_sel_hi:[0,1]
	v_add_f32_dpp v178, v178, v178 row_ror:8 row_mask:0xf bank_mask:0xf bound_ctrl:1
	v_pk_fma_f32 v[56:57], v[68:69], v[20:21], v[52:53]
	v_add_f32_dpp v172, v172, v172 row_ror:4 row_mask:0xf bank_mask:0xf bound_ctrl:1
	v_pk_fma_f32 v[58:59], v[70:71], v[22:23], v[54:55]
	v_add_f32_dpp v178, v178, v178 row_ror:4 row_mask:0xf bank_mask:0xf bound_ctrl:1
	v_lshl_add_u64 v[144:145], v[144:145], 0, v[152:153]
	v_add_f32_dpp v172, v172, v172 row_ror:2 row_mask:0xf bank_mask:0xf bound_ctrl:1
	v_lshl_add_u64 v[146:147], v[146:147], 0, v[152:153]
	v_add_f32_dpp v178, v178, v178 row_ror:2 row_mask:0xf bank_mask:0xf bound_ctrl:1
	v_lshl_add_u64 v[148:149], v[148:149], 0, v[62:63]
	v_add_f32_dpp v172, v172, v172 row_ror:1 row_mask:0xf bank_mask:0xf bound_ctrl:1
	v_add_f32_dpp v178, v178, v178 row_ror:1 row_mask:0xf bank_mask:0xf bound_ctrl:1
	v_pk_fma_f32 v[68:69], v[172:173], v[8:9], v[56:57] op_sel_hi:[0,1,1] neg_lo:[1,0,0] neg_hi:[1,0,0]
	v_pk_fma_f32 v[70:71], v[172:173], v[10:11], v[58:59] op_sel_hi:[0,1,1] neg_lo:[1,0,0] neg_hi:[1,0,0]
	v_cndmask_b32_e64 v60, v60, v178, s[22:23]
	s_waitcnt lgkmcnt(0)
	ds_read_b128 v[4:7], v156 offset:16896
	ds_read_b128 v[12:15], v156 offset:16928
	ds_read_u16_d16_hi v24, v157 offset:16896
	ds_read_b128 v[20:23], v156 offset:16960
	ds_read_b128 v[8:11], v156 offset:16912
	v_pk_mul_f32 v[174:175], v[68:69], v[28:29]
	v_pk_mul_f32 v[176:177], v[68:69], v[16:17]
	v_pk_fma_f32 v[174:175], v[70:71], v[30:31], v[174:175]
	v_pk_fma_f32 v[176:177], v[70:71], v[18:19], v[176:177]
	v_add_f32_e32 v174, v174, v175
	v_add_f32_e32 v176, v176, v177
	v_pk_mul_f32 v[52:53], v[48:49], v[36:37] op_sel_hi:[0,1]
	ds_read_b128 v[16:19], v156 offset:16944
	v_add_f32_dpp v174, v174, v174 row_ror:8 row_mask:0xf bank_mask:0xf bound_ctrl:1
	v_pk_mul_f32 v[54:55], v[48:49], v[38:39] op_sel_hi:[0,1]
	v_add_f32_dpp v176, v176, v176 row_ror:8 row_mask:0xf bank_mask:0xf bound_ctrl:1
	v_pk_fma_f32 v[56:57], v[68:69], v[44:45], v[52:53]
	v_add_f32_dpp v174, v174, v174 row_ror:4 row_mask:0xf bank_mask:0xf bound_ctrl:1
	v_pk_fma_f32 v[58:59], v[70:71], v[46:47], v[54:55]
	v_add_f32_dpp v176, v176, v176 row_ror:4 row_mask:0xf bank_mask:0xf bound_ctrl:1
	v_lshl_add_u64 v[150:151], v[150:151], 0, v[64:65]
	v_add_f32_dpp v174, v174, v174 row_ror:2 row_mask:0xf bank_mask:0xf bound_ctrl:1
	v_add_u32_e32 v158, s43, v162
	v_add_f32_dpp v176, v176, v176 row_ror:2 row_mask:0xf bank_mask:0xf bound_ctrl:1
	v_add_u32_e32 v159, s43, v163
	v_add_f32_dpp v174, v174, v174 row_ror:1 row_mask:0xf bank_mask:0xf bound_ctrl:1
	v_add_f32_dpp v176, v176, v176 row_ror:1 row_mask:0xf bank_mask:0xf bound_ctrl:1
	v_pk_fma_f32 v[68:69], v[174:175], v[32:33], v[56:57] op_sel_hi:[0,1,1] neg_lo:[1,0,0] neg_hi:[1,0,0]
	v_pk_fma_f32 v[70:71], v[174:175], v[34:35], v[58:59] op_sel_hi:[0,1,1] neg_lo:[1,0,0] neg_hi:[1,0,0]
	v_cndmask_b32_e64 v60, v60, v176, s[24:25]
	s_waitcnt lgkmcnt(0)
; DEVI void rw_chain_task(const Params& p, int l, int seq, int head, int quarter, char* smem) {
;     ...
;     for (int c = 0; c < nch; c += 4) {
;       lds_barrier();
;       RW_STORE(R1, B1);
;       RW_LOAD(R1, c + 5);
;       RW_COMPUTE(B0, c);
;       lds_barrier();
;       RW_STORE(R2, B0);
;       RW_LOAD(R2, c + 6);
;       RW_COMPUTE(B1, c + 1);
;       lds_barrier();
;       RW_STORE(R3, B1);
;       RW_LOAD(R3, c + 7);
;       RW_COMPUTE(B0, c + 2);
;       lds_barrier();
;       RW_STORE(R0, B0);
;       RW_LOAD(R0, c + 8);
;       RW_COMPUTE(B1, c + 3);
;     }
	ds_read_b128 v[28:31], v156 offset:18304
	ds_read_b128 v[36:39], v156 offset:18336
	ds_read_u16_d16_hi v48, v157 offset:18304
	ds_read_b128 v[44:47], v156 offset:18368
	ds_read_b128 v[32:35], v156 offset:18320
	v_pk_mul_f32 v[172:173], v[68:69], v[4:5]
	v_pk_mul_f32 v[178:179], v[68:69], v[40:41]
	v_pk_fma_f32 v[172:173], v[70:71], v[6:7], v[172:173]
	v_pk_fma_f32 v[178:179], v[70:71], v[42:43], v[178:179]
	v_add_f32_e32 v172, v172, v173
	v_add_f32_e32 v178, v178, v179
	v_pk_mul_f32 v[52:53], v[24:25], v[12:13] op_sel_hi:[0,1]
	ds_read_b128 v[40:43], v156 offset:18352
	v_add_f32_dpp v172, v172, v172 row_ror:8 row_mask:0xf bank_mask:0xf bound_ctrl:1
	v_pk_mul_f32 v[54:55], v[24:25], v[14:15] op_sel_hi:[0,1]
	v_add_f32_dpp v178, v178, v178 row_ror:8 row_mask:0xf bank_mask:0xf bound_ctrl:1
	v_pk_fma_f32 v[56:57], v[68:69], v[20:21], v[52:53]
	v_add_f32_dpp v172, v172, v172 row_ror:4 row_mask:0xf bank_mask:0xf bound_ctrl:1
	v_pk_fma_f32 v[58:59], v[70:71], v[22:23], v[54:55]
	v_add_f32_dpp v178, v178, v178 row_ror:4 row_mask:0xf bank_mask:0xf bound_ctrl:1
	v_add_f32_dpp v172, v172, v172 row_ror:2 row_mask:0xf bank_mask:0xf bound_ctrl:1
	s_nop 0
	v_add_f32_dpp v178, v178, v178 row_ror:2 row_mask:0xf bank_mask:0xf bound_ctrl:1
	v_add_f32_dpp v172, v172, v172 row_ror:1 row_mask:0xf bank_mask:0xf bound_ctrl:1
	s_nop 0
	v_add_f32_dpp v178, v178, v178 row_ror:1 row_mask:0xf bank_mask:0xf bound_ctrl:1
	v_pk_fma_f32 v[68:69], v[172:173], v[8:9], v[56:57] op_sel_hi:[0,1,1] neg_lo:[1,0,0] neg_hi:[1,0,0]
	v_pk_fma_f32 v[70:71], v[172:173], v[10:11], v[58:59] op_sel_hi:[0,1,1] neg_lo:[1,0,0] neg_hi:[1,0,0]
	v_cndmask_b32_e64 v60, v60, v178, s[26:27]
	s_waitcnt lgkmcnt(0)
	ds_read_b128 v[4:7], v156 offset:19712
	ds_read_b128 v[12:15], v156 offset:19744
	ds_read_u16_d16_hi v24, v157 offset:19712
	ds_read_b128 v[20:23], v156 offset:19776
	ds_read_b128 v[8:11], v156 offset:19728
	v_pk_mul_f32 v[174:175], v[68:69], v[28:29]
	v_pk_mul_f32 v[176:177], v[68:69], v[16:17]
	v_pk_fma_f32 v[174:175], v[70:71], v[30:31], v[174:175]
	v_pk_fma_f32 v[176:177], v[70:71], v[18:19], v[176:177]
	v_add_f32_e32 v174, v174, v175
	v_add_f32_e32 v176, v176, v177
	v_pk_mul_f32 v[52:53], v[48:49], v[36:37] op_sel_hi:[0,1]
	ds_read_b128 v[16:19], v156 offset:19760
	v_add_f32_dpp v174, v174, v174 row_ror:8 row_mask:0xf bank_mask:0xf bound_ctrl:1
	v_pk_mul_f32 v[54:55], v[48:49], v[38:39] op_sel_hi:[0,1]
	v_add_f32_dpp v176, v176, v176 row_ror:8 row_mask:0xf bank_mask:0xf bound_ctrl:1
	v_pk_fma_f32 v[56:57], v[68:69], v[44:45], v[52:53]
	v_add_f32_dpp v174, v174, v174 row_ror:4 row_mask:0xf bank_mask:0xf bound_ctrl:1
	v_pk_fma_f32 v[58:59], v[70:71], v[46:47], v[54:55]
	v_add_f32_dpp v176, v176, v176 row_ror:4 row_mask:0xf bank_mask:0xf bound_ctrl:1
	v_add_f32_dpp v174, v174, v174 row_ror:2 row_mask:0xf bank_mask:0xf bound_ctrl:1
	s_nop 0
	v_add_f32_dpp v176, v176, v176 row_ror:2 row_mask:0xf bank_mask:0xf bound_ctrl:1
	v_add_f32_dpp v174, v174, v174 row_ror:1 row_mask:0xf bank_mask:0xf bound_ctrl:1
	s_nop 0
	v_add_f32_dpp v176, v176, v176 row_ror:1 row_mask:0xf bank_mask:0xf bound_ctrl:1
	v_pk_fma_f32 v[68:69], v[174:175], v[32:33], v[56:57] op_sel_hi:[0,1,1] neg_lo:[1,0,0] neg_hi:[1,0,0]
	v_pk_fma_f32 v[70:71], v[174:175], v[34:35], v[58:59] op_sel_hi:[0,1,1] neg_lo:[1,0,0] neg_hi:[1,0,0]
	v_cndmask_b32_e64 v60, v60, v176, s[28:29]
	s_waitcnt lgkmcnt(0)
	ds_read_b128 v[28:31], v156 offset:21120
	ds_read_b128 v[36:39], v156 offset:21152
	ds_read_u16_d16_hi v48, v157 offset:21120
	ds_read_b128 v[44:47], v156 offset:21184
	ds_read_b128 v[32:35], v156 offset:21136
	v_pk_mul_f32 v[172:173], v[68:69], v[4:5]
	v_pk_mul_f32 v[178:179], v[68:69], v[40:41]
	v_pk_fma_f32 v[172:173], v[70:71], v[6:7], v[172:173]
	v_pk_fma_f32 v[178:179], v[70:71], v[42:43], v[178:179]
	v_add_f32_e32 v172, v172, v173
	v_add_f32_e32 v178, v178, v179
	v_pk_mul_f32 v[52:53], v[24:25], v[12:13] op_sel_hi:[0,1]
	ds_read_b128 v[40:43], v156 offset:21168
	v_add_f32_dpp v172, v172, v172 row_ror:8 row_mask:0xf bank_mask:0xf bound_ctrl:1
	v_pk_mul_f32 v[54:55], v[24:25], v[14:15] op_sel_hi:[0,1]
	v_add_f32_dpp v178, v178, v178 row_ror:8 row_mask:0xf bank_mask:0xf bound_ctrl:1
	v_pk_fma_f32 v[56:57], v[68:69], v[20:21], v[52:53]
	v_add_f32_dpp v172, v172, v172 row_ror:4 row_mask:0xf bank_mask:0xf bound_ctrl:1
	v_pk_fma_f32 v[58:59], v[70:71], v[22:23], v[54:55]
	v_add_f32_dpp v178, v178, v178 row_ror:4 row_mask:0xf bank_mask:0xf bound_ctrl:1
	v_add_f32_dpp v172, v172, v172 row_ror:2 row_mask:0xf bank_mask:0xf bound_ctrl:1
	s_nop 0
	v_add_f32_dpp v178, v178, v178 row_ror:2 row_mask:0xf bank_mask:0xf bound_ctrl:1
	v_add_f32_dpp v172, v172, v172 row_ror:1 row_mask:0xf bank_mask:0xf bound_ctrl:1
	s_nop 0
	v_add_f32_dpp v178, v178, v178 row_ror:1 row_mask:0xf bank_mask:0xf bound_ctrl:1
	v_pk_fma_f32 v[68:69], v[172:173], v[8:9], v[56:57] op_sel_hi:[0,1,1] neg_lo:[1,0,0] neg_hi:[1,0,0]
	v_pk_fma_f32 v[70:71], v[172:173], v[10:11], v[58:59] op_sel_hi:[0,1,1] neg_lo:[1,0,0] neg_hi:[1,0,0]
	v_cndmask_b32_e64 v60, v60, v178, s[30:31]
	s_waitcnt lgkmcnt(0)
	ds_read_b128 v[4:7], v158 offset:0
	ds_read_b128 v[12:15], v158 offset:32
	ds_read_u16_d16_hi v24, v159 offset:0
	ds_read_b128 v[20:23], v158 offset:64
	ds_read_b128 v[8:11], v158 offset:16
	v_pk_mul_f32 v[174:175], v[68:69], v[28:29]
	v_pk_mul_f32 v[176:177], v[68:69], v[16:17]
	v_pk_fma_f32 v[174:175], v[70:71], v[30:31], v[174:175]
	v_pk_fma_f32 v[176:177], v[70:71], v[18:19], v[176:177]
	v_add_f32_e32 v174, v174, v175
	v_add_f32_e32 v176, v176, v177
	v_pk_mul_f32 v[52:53], v[48:49], v[36:37] op_sel_hi:[0,1]
	ds_read_b128 v[16:19], v158 offset:48
	v_add_f32_dpp v174, v174, v174 row_ror:8 row_mask:0xf bank_mask:0xf bound_ctrl:1
	v_pk_mul_f32 v[54:55], v[48:49], v[38:39] op_sel_hi:[0,1]
	v_add_f32_dpp v176, v176, v176 row_ror:8 row_mask:0xf bank_mask:0xf bound_ctrl:1
	v_pk_fma_f32 v[56:57], v[68:69], v[44:45], v[52:53]
	v_add_f32_dpp v174, v174, v174 row_ror:4 row_mask:0xf bank_mask:0xf bound_ctrl:1
	v_pk_fma_f32 v[58:59], v[70:71], v[46:47], v[54:55]
	v_add_f32_dpp v176, v176, v176 row_ror:4 row_mask:0xf bank_mask:0xf bound_ctrl:1
	v_add_f32_dpp v174, v174, v174 row_ror:2 row_mask:0xf bank_mask:0xf bound_ctrl:1
	s_nop 0
	v_add_f32_dpp v176, v176, v176 row_ror:2 row_mask:0xf bank_mask:0xf bound_ctrl:1
	v_add_f32_dpp v174, v174, v174 row_ror:1 row_mask:0xf bank_mask:0xf bound_ctrl:1
	s_nop 0
	v_add_f32_dpp v176, v176, v176 row_ror:1 row_mask:0xf bank_mask:0xf bound_ctrl:1
	v_pk_fma_f32 v[68:69], v[174:175], v[32:33], v[56:57] op_sel_hi:[0,1,1] neg_lo:[1,0,0] neg_hi:[1,0,0]
	v_pk_fma_f32 v[70:71], v[174:175], v[34:35], v[58:59] op_sel_hi:[0,1,1] neg_lo:[1,0,0] neg_hi:[1,0,0]
	v_cndmask_b32_e64 v60, v60, v176, s[34:35]
	s_waitcnt lgkmcnt(0)
	s_barrier
	s_mov_b32 vcc_lo, s42
	s_mov_b32 s42, s43
	s_mov_b32 s43, s45
	s_mov_b32 s45, vcc_lo
	v_add_u32_e32 v156, s42, v162
	v_add_u32_e32 v157, s42, v163
	v_add_u32_e32 v155, s45, v164
	v_add_u32_e32 v165, s45, v167
	v_add_u32_e32 v166, s45, v168
	s_waitcnt lgkmcnt(0)
	ds_read_b128 v[28:31], v156 offset:1408
	ds_read_b128 v[36:39], v156 offset:1440
	ds_read_u16_d16_hi v48, v157 offset:1408
	ds_read_b128 v[44:47], v156 offset:1472
	ds_read_b128 v[32:35], v156 offset:1424
	v_pk_mul_f32 v[172:173], v[68:69], v[4:5]
	v_pk_mul_f32 v[178:179], v[68:69], v[40:41]
	v_pk_fma_f32 v[172:173], v[70:71], v[6:7], v[172:173]
	v_pk_fma_f32 v[178:179], v[70:71], v[42:43], v[178:179]
	v_add_f32_e32 v172, v172, v173
	v_add_f32_e32 v178, v178, v179
	v_pk_mul_f32 v[52:53], v[24:25], v[12:13] op_sel_hi:[0,1]
	ds_read_b128 v[40:43], v156 offset:1456
	v_add_f32_dpp v172, v172, v172 row_ror:8 row_mask:0xf bank_mask:0xf bound_ctrl:1
	v_pk_mul_f32 v[54:55], v[24:25], v[14:15] op_sel_hi:[0,1]
	v_add_f32_dpp v178, v178, v178 row_ror:8 row_mask:0xf bank_mask:0xf bound_ctrl:1
	v_pk_fma_f32 v[56:57], v[68:69], v[20:21], v[52:53]
	v_add_f32_dpp v172, v172, v172 row_ror:4 row_mask:0xf bank_mask:0xf bound_ctrl:1
	v_pk_fma_f32 v[58:59], v[70:71], v[22:23], v[54:55]
	v_add_f32_dpp v178, v178, v178 row_ror:4 row_mask:0xf bank_mask:0xf bound_ctrl:1
	v_add_f32_dpp v172, v172, v172 row_ror:2 row_mask:0xf bank_mask:0xf bound_ctrl:1
	s_nop 0
	v_add_f32_dpp v178, v178, v178 row_ror:2 row_mask:0xf bank_mask:0xf bound_ctrl:1
	v_add_f32_dpp v172, v172, v172 row_ror:1 row_mask:0xf bank_mask:0xf bound_ctrl:1
	s_nop 0
	v_add_f32_dpp v178, v178, v178 row_ror:1 row_mask:0xf bank_mask:0xf bound_ctrl:1
	v_pk_fma_f32 v[68:69], v[172:173], v[8:9], v[56:57] op_sel_hi:[0,1,1] neg_lo:[1,0,0] neg_hi:[1,0,0]
	v_pk_fma_f32 v[70:71], v[172:173], v[10:11], v[58:59] op_sel_hi:[0,1,1] neg_lo:[1,0,0] neg_hi:[1,0,0]
	v_cndmask_b32_e64 v60, v60, v178, s[36:37]
	v_bfe_u32 v61, v60, 16, 1
	v_add3_u32 v61, v60, v61, s33
	global_store_short_d16_hi v[160:161], v61, off
	v_lshl_add_u64 v[160:161], v[160:161], 0, s[46:47]
	s_waitcnt lgkmcnt(0)
	ds_read_b128 v[4:7], v156 offset:2816
	ds_read_b128 v[12:15], v156 offset:2848
	ds_read_u16_d16_hi v24, v157 offset:2816
	ds_read_b128 v[20:23], v156 offset:2880
	ds_read_b128 v[8:11], v156 offset:2832
	v_pk_mul_f32 v[174:175], v[68:69], v[28:29]
	v_pk_mul_f32 v[176:177], v[68:69], v[16:17]
	v_pk_fma_f32 v[174:175], v[70:71], v[30:31], v[174:175]
	v_pk_fma_f32 v[176:177], v[70:71], v[18:19], v[176:177]
	v_add_f32_e32 v174, v174, v175
	v_add_f32_e32 v176, v176, v177
	v_pk_mul_f32 v[52:53], v[48:49], v[36:37] op_sel_hi:[0,1]
	ds_read_b128 v[16:19], v156 offset:2864
	v_add_f32_dpp v174, v174, v174 row_ror:8 row_mask:0xf bank_mask:0xf bound_ctrl:1
	v_pk_mul_f32 v[54:55], v[48:49], v[38:39] op_sel_hi:[0,1]
	v_add_f32_dpp v176, v176, v176 row_ror:8 row_mask:0xf bank_mask:0xf bound_ctrl:1
	v_pk_fma_f32 v[56:57], v[68:69], v[44:45], v[52:53]
	v_add_f32_dpp v174, v174, v174 row_ror:4 row_mask:0xf bank_mask:0xf bound_ctrl:1
	v_pk_fma_f32 v[58:59], v[70:71], v[46:47], v[54:55]
	v_add_f32_dpp v176, v176, v176 row_ror:4 row_mask:0xf bank_mask:0xf bound_ctrl:1
	s_waitcnt vmcnt(12)
	v_add_f32_dpp v174, v174, v174 row_ror:2 row_mask:0xf bank_mask:0xf bound_ctrl:1
	v_lshlrev_b32_e32 v136, 16, v72
	v_add_f32_dpp v176, v176, v176 row_ror:2 row_mask:0xf bank_mask:0xf bound_ctrl:1
	v_and_b32_e32 v137, 0xffff0000, v72
	v_add_f32_dpp v174, v174, v174 row_ror:1 row_mask:0xf bank_mask:0xf bound_ctrl:1
	v_add_f32_dpp v176, v176, v176 row_ror:1 row_mask:0xf bank_mask:0xf bound_ctrl:1
	v_pk_fma_f32 v[68:69], v[174:175], v[32:33], v[56:57] op_sel_hi:[0,1,1] neg_lo:[1,0,0] neg_hi:[1,0,0]
	v_pk_fma_f32 v[70:71], v[174:175], v[34:35], v[58:59] op_sel_hi:[0,1,1] neg_lo:[1,0,0] neg_hi:[1,0,0]
	v_cndmask_b32_e64 v60, v60, v176, s[4:5]
	s_waitcnt lgkmcnt(0)
	ds_read_b128 v[28:31], v156 offset:4224
	ds_read_b128 v[36:39], v156 offset:4256
	ds_read_u16_d16_hi v48, v157 offset:4224
	ds_read_b128 v[44:47], v156 offset:4288
	ds_read_b128 v[32:35], v156 offset:4240
	v_pk_mul_f32 v[172:173], v[68:69], v[4:5]
	v_pk_mul_f32 v[178:179], v[68:69], v[40:41]
	v_pk_fma_f32 v[172:173], v[70:71], v[6:7], v[172:173]
	v_pk_fma_f32 v[178:179], v[70:71], v[42:43], v[178:179]
	v_add_f32_e32 v172, v172, v173
	v_add_f32_e32 v178, v178, v179
	v_pk_mul_f32 v[52:53], v[24:25], v[12:13] op_sel_hi:[0,1]
	ds_read_b128 v[40:43], v156 offset:4272
	v_add_f32_dpp v172, v172, v172 row_ror:8 row_mask:0xf bank_mask:0xf bound_ctrl:1
	v_pk_mul_f32 v[54:55], v[24:25], v[14:15] op_sel_hi:[0,1]
	v_add_f32_dpp v178, v178, v178 row_ror:8 row_mask:0xf bank_mask:0xf bound_ctrl:1
	v_pk_fma_f32 v[56:57], v[68:69], v[20:21], v[52:53]
	v_add_f32_dpp v172, v172, v172 row_ror:4 row_mask:0xf bank_mask:0xf bound_ctrl:1
	v_pk_fma_f32 v[58:59], v[70:71], v[22:23], v[54:55]
	v_add_f32_dpp v178, v178, v178 row_ror:4 row_mask:0xf bank_mask:0xf bound_ctrl:1
	v_lshlrev_b32_e32 v138, 16, v73
	v_add_f32_dpp v172, v172, v172 row_ror:2 row_mask:0xf bank_mask:0xf bound_ctrl:1
	v_and_b32_e32 v139, 0xffff0000, v73
	v_add_f32_dpp v178, v178, v178 row_ror:2 row_mask:0xf bank_mask:0xf bound_ctrl:1
	v_lshlrev_b32_e32 v140, 16, v74
	v_add_f32_dpp v172, v172, v172 row_ror:1 row_mask:0xf bank_mask:0xf bound_ctrl:1
	v_add_f32_dpp v178, v178, v178 row_ror:1 row_mask:0xf bank_mask:0xf bound_ctrl:1
	v_pk_fma_f32 v[68:69], v[172:173], v[8:9], v[56:57] op_sel_hi:[0,1,1] neg_lo:[1,0,0] neg_hi:[1,0,0]
	v_pk_fma_f32 v[70:71], v[172:173], v[10:11], v[58:59] op_sel_hi:[0,1,1] neg_lo:[1,0,0] neg_hi:[1,0,0]
	v_cndmask_b32_e64 v60, v60, v178, s[6:7]
	s_waitcnt lgkmcnt(0)
	ds_read_b128 v[4:7], v156 offset:5632
	ds_read_b128 v[12:15], v156 offset:5664
	ds_read_u16_d16_hi v24, v157 offset:5632
	ds_read_b128 v[20:23], v156 offset:5696
	ds_read_b128 v[8:11], v156 offset:5648
	v_pk_mul_f32 v[174:175], v[68:69], v[28:29]
	v_pk_mul_f32 v[176:177], v[68:69], v[16:17]
	v_pk_fma_f32 v[174:175], v[70:71], v[30:31], v[174:175]
	v_pk_fma_f32 v[176:177], v[70:71], v[18:19], v[176:177]
	v_add_f32_e32 v174, v174, v175
	v_add_f32_e32 v176, v176, v177
	v_pk_mul_f32 v[52:53], v[48:49], v[36:37] op_sel_hi:[0,1]
	ds_read_b128 v[16:19], v156 offset:5680
	v_add_f32_dpp v174, v174, v174 row_ror:8 row_mask:0xf bank_mask:0xf bound_ctrl:1
	v_pk_mul_f32 v[54:55], v[48:49], v[38:39] op_sel_hi:[0,1]
	v_add_f32_dpp v176, v176, v176 row_ror:8 row_mask:0xf bank_mask:0xf bound_ctrl:1
	v_pk_fma_f32 v[56:57], v[68:69], v[44:45], v[52:53]
	v_add_f32_dpp v174, v174, v174 row_ror:4 row_mask:0xf bank_mask:0xf bound_ctrl:1
	v_pk_fma_f32 v[58:59], v[70:71], v[46:47], v[54:55]
	v_add_f32_dpp v176, v176, v176 row_ror:4 row_mask:0xf bank_mask:0xf bound_ctrl:1
	v_and_b32_e32 v141, 0xffff0000, v74
	v_add_f32_dpp v174, v174, v174 row_ror:2 row_mask:0xf bank_mask:0xf bound_ctrl:1
	v_lshlrev_b32_e32 v142, 16, v75
	v_add_f32_dpp v176, v176, v176 row_ror:2 row_mask:0xf bank_mask:0xf bound_ctrl:1
	v_and_b32_e32 v143, 0xffff0000, v75
	v_add_f32_dpp v174, v174, v174 row_ror:1 row_mask:0xf bank_mask:0xf bound_ctrl:1
	v_add_f32_dpp v176, v176, v176 row_ror:1 row_mask:0xf bank_mask:0xf bound_ctrl:1
	v_pk_fma_f32 v[68:69], v[174:175], v[32:33], v[56:57] op_sel_hi:[0,1,1] neg_lo:[1,0,0] neg_hi:[1,0,0]
	v_pk_fma_f32 v[70:71], v[174:175], v[34:35], v[58:59] op_sel_hi:[0,1,1] neg_lo:[1,0,0] neg_hi:[1,0,0]
	v_cndmask_b32_e64 v60, v60, v176, s[8:9]
	s_waitcnt lgkmcnt(0)
	ds_read_b128 v[28:31], v156 offset:7040
	ds_read_b128 v[36:39], v156 offset:7072
	ds_read_u16_d16_hi v48, v157 offset:7040
	ds_read_b128 v[44:47], v156 offset:7104
	ds_read_b128 v[32:35], v156 offset:7056
	v_pk_mul_f32 v[172:173], v[68:69], v[4:5]
	v_pk_mul_f32 v[178:179], v[68:69], v[40:41]
	v_pk_fma_f32 v[172:173], v[70:71], v[6:7], v[172:173]
	v_pk_fma_f32 v[178:179], v[70:71], v[42:43], v[178:179]
	v_add_f32_e32 v172, v172, v173
	v_add_f32_e32 v178, v178, v179
	v_pk_mul_f32 v[52:53], v[24:25], v[12:13] op_sel_hi:[0,1]
	ds_read_b128 v[40:43], v156 offset:7088
	v_add_f32_dpp v172, v172, v172 row_ror:8 row_mask:0xf bank_mask:0xf bound_ctrl:1
	v_pk_mul_f32 v[54:55], v[24:25], v[14:15] op_sel_hi:[0,1]
	v_add_f32_dpp v178, v178, v178 row_ror:8 row_mask:0xf bank_mask:0xf bound_ctrl:1
	v_pk_fma_f32 v[56:57], v[68:69], v[20:21], v[52:53]
	v_add_f32_dpp v172, v172, v172 row_ror:4 row_mask:0xf bank_mask:0xf bound_ctrl:1
	v_pk_fma_f32 v[58:59], v[70:71], v[22:23], v[54:55]
	v_add_f32_dpp v178, v178, v178 row_ror:4 row_mask:0xf bank_mask:0xf bound_ctrl:1
	ds_write_b128 v155, v[136:139] offset:0
	v_add_f32_dpp v172, v172, v172 row_ror:2 row_mask:0xf bank_mask:0xf bound_ctrl:1
	ds_write_b128 v155, v[140:143] offset:80
	v_add_f32_dpp v178, v178, v178 row_ror:2 row_mask:0xf bank_mask:0xf bound_ctrl:1
	v_lshlrev_b32_e32 v136, 16, v76
	v_add_f32_dpp v172, v172, v172 row_ror:1 row_mask:0xf bank_mask:0xf bound_ctrl:1
	v_add_f32_dpp v178, v178, v178 row_ror:1 row_mask:0xf bank_mask:0xf bound_ctrl:1
	v_pk_fma_f32 v[68:69], v[172:173], v[8:9], v[56:57] op_sel_hi:[0,1,1] neg_lo:[1,0,0] neg_hi:[1,0,0]
	v_pk_fma_f32 v[70:71], v[172:173], v[10:11], v[58:59] op_sel_hi:[0,1,1] neg_lo:[1,0,0] neg_hi:[1,0,0]
	v_cndmask_b32_e64 v60, v60, v178, s[10:11]
	s_waitcnt lgkmcnt(2)
	ds_read_b128 v[4:7], v156 offset:8448
	ds_read_b128 v[12:15], v156 offset:8480
	ds_read_u16_d16_hi v24, v157 offset:8448
	ds_read_b128 v[20:23], v156 offset:8512
	ds_read_b128 v[8:11], v156 offset:8464
	v_pk_mul_f32 v[174:175], v[68:69], v[28:29]
	v_pk_mul_f32 v[176:177], v[68:69], v[16:17]
	v_pk_fma_f32 v[174:175], v[70:71], v[30:31], v[174:175]
	v_pk_fma_f32 v[176:177], v[70:71], v[18:19], v[176:177]
	v_add_f32_e32 v174, v174, v175
	v_add_f32_e32 v176, v176, v177
	v_pk_mul_f32 v[52:53], v[48:49], v[36:37] op_sel_hi:[0,1]
	ds_read_b128 v[16:19], v156 offset:8496
	v_add_f32_dpp v174, v174, v174 row_ror:8 row_mask:0xf bank_mask:0xf bound_ctrl:1
	v_pk_mul_f32 v[54:55], v[48:49], v[38:39] op_sel_hi:[0,1]
	v_add_f32_dpp v176, v176, v176 row_ror:8 row_mask:0xf bank_mask:0xf bound_ctrl:1
	v_pk_fma_f32 v[56:57], v[68:69], v[44:45], v[52:53]
	v_add_f32_dpp v174, v174, v174 row_ror:4 row_mask:0xf bank_mask:0xf bound_ctrl:1
	v_pk_fma_f32 v[58:59], v[70:71], v[46:47], v[54:55]
	v_add_f32_dpp v176, v176, v176 row_ror:4 row_mask:0xf bank_mask:0xf bound_ctrl:1
	v_and_b32_e32 v137, 0xffff0000, v76
	v_add_f32_dpp v174, v174, v174 row_ror:2 row_mask:0xf bank_mask:0xf bound_ctrl:1
	v_lshlrev_b32_e32 v138, 16, v77
	v_add_f32_dpp v176, v176, v176 row_ror:2 row_mask:0xf bank_mask:0xf bound_ctrl:1
	v_and_b32_e32 v139, 0xffff0000, v77
	v_add_f32_dpp v174, v174, v174 row_ror:1 row_mask:0xf bank_mask:0xf bound_ctrl:1
	v_add_f32_dpp v176, v176, v176 row_ror:1 row_mask:0xf bank_mask:0xf bound_ctrl:1
	v_pk_fma_f32 v[68:69], v[174:175], v[32:33], v[56:57] op_sel_hi:[0,1,1] neg_lo:[1,0,0] neg_hi:[1,0,0]
	v_pk_fma_f32 v[70:71], v[174:175], v[34:35], v[58:59] op_sel_hi:[0,1,1] neg_lo:[1,0,0] neg_hi:[1,0,0]
	v_cndmask_b32_e64 v60, v60, v176, s[12:13]
	s_waitcnt lgkmcnt(0)
	ds_read_b128 v[28:31], v156 offset:9856
	ds_read_b128 v[36:39], v156 offset:9888
	ds_read_u16_d16_hi v48, v157 offset:9856
	ds_read_b128 v[44:47], v156 offset:9920
	ds_read_b128 v[32:35], v156 offset:9872
	v_pk_mul_f32 v[172:173], v[68:69], v[4:5]
	v_pk_mul_f32 v[178:179], v[68:69], v[40:41]
	v_pk_fma_f32 v[172:173], v[70:71], v[6:7], v[172:173]
	v_pk_fma_f32 v[178:179], v[70:71], v[42:43], v[178:179]
	v_add_f32_e32 v172, v172, v173
	v_add_f32_e32 v178, v178, v179
	v_pk_mul_f32 v[52:53], v[24:25], v[12:13] op_sel_hi:[0,1]
	ds_read_b128 v[40:43], v156 offset:9904
	v_add_f32_dpp v172, v172, v172 row_ror:8 row_mask:0xf bank_mask:0xf bound_ctrl:1
	v_pk_mul_f32 v[54:55], v[24:25], v[14:15] op_sel_hi:[0,1]
	v_add_f32_dpp v178, v178, v178 row_ror:8 row_mask:0xf bank_mask:0xf bound_ctrl:1
	v_pk_fma_f32 v[56:57], v[68:69], v[20:21], v[52:53]
	v_add_f32_dpp v172, v172, v172 row_ror:4 row_mask:0xf bank_mask:0xf bound_ctrl:1
	v_pk_fma_f32 v[58:59], v[70:71], v[22:23], v[54:55]
	v_add_f32_dpp v178, v178, v178 row_ror:4 row_mask:0xf bank_mask:0xf bound_ctrl:1
	v_lshlrev_b32_e32 v140, 16, v78
	v_add_f32_dpp v172, v172, v172 row_ror:2 row_mask:0xf bank_mask:0xf bound_ctrl:1
	v_and_b32_e32 v141, 0xffff0000, v78
	v_add_f32_dpp v178, v178, v178 row_ror:2 row_mask:0xf bank_mask:0xf bound_ctrl:1
	v_lshlrev_b32_e32 v142, 16, v79
	v_add_f32_dpp v172, v172, v172 row_ror:1 row_mask:0xf bank_mask:0xf bound_ctrl:1
	v_add_f32_dpp v178, v178, v178 row_ror:1 row_mask:0xf bank_mask:0xf bound_ctrl:1
	v_pk_fma_f32 v[68:69], v[172:173], v[8:9], v[56:57] op_sel_hi:[0,1,1] neg_lo:[1,0,0] neg_hi:[1,0,0]
	v_pk_fma_f32 v[70:71], v[172:173], v[10:11], v[58:59] op_sel_hi:[0,1,1] neg_lo:[1,0,0] neg_hi:[1,0,0]
	v_cndmask_b32_e64 v60, v60, v178, s[14:15]
	s_waitcnt lgkmcnt(0)
	ds_read_b128 v[4:7], v156 offset:11264
	ds_read_b128 v[12:15], v156 offset:11296
	ds_read_u16_d16_hi v24, v157 offset:11264
	ds_read_b128 v[20:23], v156 offset:11328
	ds_read_b128 v[8:11], v156 offset:11280
	v_pk_mul_f32 v[174:175], v[68:69], v[28:29]
	v_pk_mul_f32 v[176:177], v[68:69], v[16:17]
	v_pk_fma_f32 v[174:175], v[70:71], v[30:31], v[174:175]
	v_pk_fma_f32 v[176:177], v[70:71], v[18:19], v[176:177]
	v_add_f32_e32 v174, v174, v175
	v_add_f32_e32 v176, v176, v177
	v_pk_mul_f32 v[52:53], v[48:49], v[36:37] op_sel_hi:[0,1]
	ds_read_b128 v[16:19], v156 offset:11312
	v_add_f32_dpp v174, v174, v174 row_ror:8 row_mask:0xf bank_mask:0xf bound_ctrl:1
	v_pk_mul_f32 v[54:55], v[48:49], v[38:39] op_sel_hi:[0,1]
	v_add_f32_dpp v176, v176, v176 row_ror:8 row_mask:0xf bank_mask:0xf bound_ctrl:1
	v_pk_fma_f32 v[56:57], v[68:69], v[44:45], v[52:53]
	v_add_f32_dpp v174, v174, v174 row_ror:4 row_mask:0xf bank_mask:0xf bound_ctrl:1
	v_pk_fma_f32 v[58:59], v[70:71], v[46:47], v[54:55]
	v_add_f32_dpp v176, v176, v176 row_ror:4 row_mask:0xf bank_mask:0xf bound_ctrl:1
	v_and_b32_e32 v143, 0xffff0000, v79
	v_add_f32_dpp v174, v174, v174 row_ror:2 row_mask:0xf bank_mask:0xf bound_ctrl:1
	ds_write_b128 v155, v[136:139] offset:11264
	v_add_f32_dpp v176, v176, v176 row_ror:2 row_mask:0xf bank_mask:0xf bound_ctrl:1
	ds_write_b128 v155, v[140:143] offset:11344
	v_add_f32_dpp v174, v174, v174 row_ror:1 row_mask:0xf bank_mask:0xf bound_ctrl:1
	v_add_f32_dpp v176, v176, v176 row_ror:1 row_mask:0xf bank_mask:0xf bound_ctrl:1
	v_pk_fma_f32 v[68:69], v[174:175], v[32:33], v[56:57] op_sel_hi:[0,1,1] neg_lo:[1,0,0] neg_hi:[1,0,0]
	v_pk_fma_f32 v[70:71], v[174:175], v[34:35], v[58:59] op_sel_hi:[0,1,1] neg_lo:[1,0,0] neg_hi:[1,0,0]
	v_cndmask_b32_e64 v60, v60, v176, s[16:17]
	s_waitcnt lgkmcnt(2)
	ds_read_b128 v[28:31], v156 offset:12672
	ds_read_b128 v[36:39], v156 offset:12704
	ds_read_u16_d16_hi v48, v157 offset:12672
	ds_read_b128 v[44:47], v156 offset:12736
	ds_read_b128 v[32:35], v156 offset:12688
	v_pk_mul_f32 v[172:173], v[68:69], v[4:5]
	v_pk_mul_f32 v[178:179], v[68:69], v[40:41]
	v_pk_fma_f32 v[172:173], v[70:71], v[6:7], v[172:173]
	v_pk_fma_f32 v[178:179], v[70:71], v[42:43], v[178:179]
	v_add_f32_e32 v172, v172, v173
	v_add_f32_e32 v178, v178, v179
	v_pk_mul_f32 v[52:53], v[24:25], v[12:13] op_sel_hi:[0,1]
	ds_read_b128 v[40:43], v156 offset:12720
	v_add_f32_dpp v172, v172, v172 row_ror:8 row_mask:0xf bank_mask:0xf bound_ctrl:1
	v_pk_mul_f32 v[54:55], v[24:25], v[14:15] op_sel_hi:[0,1]
	v_add_f32_dpp v178, v178, v178 row_ror:8 row_mask:0xf bank_mask:0xf bound_ctrl:1
	v_pk_fma_f32 v[56:57], v[68:69], v[20:21], v[52:53]
	v_add_f32_dpp v172, v172, v172 row_ror:4 row_mask:0xf bank_mask:0xf bound_ctrl:1
	v_pk_fma_f32 v[58:59], v[70:71], v[22:23], v[54:55]
	v_add_f32_dpp v178, v178, v178 row_ror:4 row_mask:0xf bank_mask:0xf bound_ctrl:1
	ds_write_b128 v165, v[80:83]
	v_add_f32_dpp v172, v172, v172 row_ror:2 row_mask:0xf bank_mask:0xf bound_ctrl:1
	ds_write_b128 v166, v[84:87]
	v_add_f32_dpp v178, v178, v178 row_ror:2 row_mask:0xf bank_mask:0xf bound_ctrl:1
	global_load_dwordx4 v[72:75], v[144:145], off
	v_add_f32_dpp v172, v172, v172 row_ror:1 row_mask:0xf bank_mask:0xf bound_ctrl:1
	v_add_f32_dpp v178, v178, v178 row_ror:1 row_mask:0xf bank_mask:0xf bound_ctrl:1
	v_pk_fma_f32 v[68:69], v[172:173], v[8:9], v[56:57] op_sel_hi:[0,1,1] neg_lo:[1,0,0] neg_hi:[1,0,0]
	v_pk_fma_f32 v[70:71], v[172:173], v[10:11], v[58:59] op_sel_hi:[0,1,1] neg_lo:[1,0,0] neg_hi:[1,0,0]
	v_cndmask_b32_e64 v60, v60, v178, s[18:19]
	s_waitcnt lgkmcnt(2)
	ds_read_b128 v[4:7], v156 offset:14080
	ds_read_b128 v[12:15], v156 offset:14112
	ds_read_u16_d16_hi v24, v157 offset:14080
	ds_read_b128 v[20:23], v156 offset:14144
	ds_read_b128 v[8:11], v156 offset:14096
	v_pk_mul_f32 v[174:175], v[68:69], v[28:29]
	v_pk_mul_f32 v[176:177], v[68:69], v[16:17]
	v_pk_fma_f32 v[174:175], v[70:71], v[30:31], v[174:175]
	v_pk_fma_f32 v[176:177], v[70:71], v[18:19], v[176:177]
	v_add_f32_e32 v174, v174, v175
	v_add_f32_e32 v176, v176, v177
	v_pk_mul_f32 v[52:53], v[48:49], v[36:37] op_sel_hi:[0,1]
	ds_read_b128 v[16:19], v156 offset:14128
	v_add_f32_dpp v174, v174, v174 row_ror:8 row_mask:0xf bank_mask:0xf bound_ctrl:1
	v_pk_mul_f32 v[54:55], v[48:49], v[38:39] op_sel_hi:[0,1]
	v_add_f32_dpp v176, v176, v176 row_ror:8 row_mask:0xf bank_mask:0xf bound_ctrl:1
	v_pk_fma_f32 v[56:57], v[68:69], v[44:45], v[52:53]
	v_add_f32_dpp v174, v174, v174 row_ror:4 row_mask:0xf bank_mask:0xf bound_ctrl:1
	v_pk_fma_f32 v[58:59], v[70:71], v[46:47], v[54:55]
	v_add_f32_dpp v176, v176, v176 row_ror:4 row_mask:0xf bank_mask:0xf bound_ctrl:1
	global_load_dwordx4 v[76:79], v[146:147], off
	v_add_f32_dpp v174, v174, v174 row_ror:2 row_mask:0xf bank_mask:0xf bound_ctrl:1
	global_load_dwordx4 v[80:83], v[148:149], off
	v_add_f32_dpp v176, v176, v176 row_ror:2 row_mask:0xf bank_mask:0xf bound_ctrl:1
	global_load_dwordx4 v[84:87], v[150:151], off
	v_add_f32_dpp v174, v174, v174 row_ror:1 row_mask:0xf bank_mask:0xf bound_ctrl:1
	v_add_f32_dpp v176, v176, v176 row_ror:1 row_mask:0xf bank_mask:0xf bound_ctrl:1
	v_pk_fma_f32 v[68:69], v[174:175], v[32:33], v[56:57] op_sel_hi:[0,1,1] neg_lo:[1,0,0] neg_hi:[1,0,0]
	v_pk_fma_f32 v[70:71], v[174:175], v[34:35], v[58:59] op_sel_hi:[0,1,1] neg_lo:[1,0,0] neg_hi:[1,0,0]
	v_cndmask_b32_e64 v60, v60, v176, s[20:21]
	s_waitcnt lgkmcnt(0)
	ds_read_b128 v[28:31], v156 offset:15488
	ds_read_b128 v[36:39], v156 offset:15520
	ds_read_u16_d16_hi v48, v157 offset:15488
	ds_read_b128 v[44:47], v156 offset:15552
	ds_read_b128 v[32:35], v156 offset:15504
	v_pk_mul_f32 v[172:173], v[68:69], v[4:5]
	v_pk_mul_f32 v[178:179], v[68:69], v[40:41]
	v_pk_fma_f32 v[172:173], v[70:71], v[6:7], v[172:173]
	v_pk_fma_f32 v[178:179], v[70:71], v[42:43], v[178:179]
	v_add_f32_e32 v172, v172, v173
	v_add_f32_e32 v178, v178, v179
	v_pk_mul_f32 v[52:53], v[24:25], v[12:13] op_sel_hi:[0,1]
	ds_read_b128 v[40:43], v156 offset:15536
	v_add_f32_dpp v172, v172, v172 row_ror:8 row_mask:0xf bank_mask:0xf bound_ctrl:1
	v_pk_mul_f32 v[54:55], v[24:25], v[14:15] op_sel_hi:[0,1]
	v_add_f32_dpp v178, v178, v178 row_ror:8 row_mask:0xf bank_mask:0xf bound_ctrl:1
	v_pk_fma_f32 v[56:57], v[68:69], v[20:21], v[52:53]
	v_add_f32_dpp v172, v172, v172 row_ror:4 row_mask:0xf bank_mask:0xf bound_ctrl:1
	v_pk_fma_f32 v[58:59], v[70:71], v[22:23], v[54:55]
	v_add_f32_dpp v178, v178, v178 row_ror:4 row_mask:0xf bank_mask:0xf bound_ctrl:1
	v_lshl_add_u64 v[144:145], v[144:145], 0, v[152:153]
	v_add_f32_dpp v172, v172, v172 row_ror:2 row_mask:0xf bank_mask:0xf bound_ctrl:1
	v_lshl_add_u64 v[146:147], v[146:147], 0, v[152:153]
	v_add_f32_dpp v178, v178, v178 row_ror:2 row_mask:0xf bank_mask:0xf bound_ctrl:1
	v_lshl_add_u64 v[148:149], v[148:149], 0, v[62:63]
	v_add_f32_dpp v172, v172, v172 row_ror:1 row_mask:0xf bank_mask:0xf bound_ctrl:1
	v_add_f32_dpp v178, v178, v178 row_ror:1 row_mask:0xf bank_mask:0xf bound_ctrl:1
	v_pk_fma_f32 v[68:69], v[172:173], v[8:9], v[56:57] op_sel_hi:[0,1,1] neg_lo:[1,0,0] neg_hi:[1,0,0]
	v_pk_fma_f32 v[70:71], v[172:173], v[10:11], v[58:59] op_sel_hi:[0,1,1] neg_lo:[1,0,0] neg_hi:[1,0,0]
	v_cndmask_b32_e64 v60, v60, v178, s[22:23]
	s_waitcnt lgkmcnt(0)
	ds_read_b128 v[4:7], v156 offset:16896
	ds_read_b128 v[12:15], v156 offset:16928
	ds_read_u16_d16_hi v24, v157 offset:16896
	ds_read_b128 v[20:23], v156 offset:16960
	ds_read_b128 v[8:11], v156 offset:16912
	v_pk_mul_f32 v[174:175], v[68:69], v[28:29]
	v_pk_mul_f32 v[176:177], v[68:69], v[16:17]
	v_pk_fma_f32 v[174:175], v[70:71], v[30:31], v[174:175]
	v_pk_fma_f32 v[176:177], v[70:71], v[18:19], v[176:177]
	v_add_f32_e32 v174, v174, v175
	v_add_f32_e32 v176, v176, v177
	v_pk_mul_f32 v[52:53], v[48:49], v[36:37] op_sel_hi:[0,1]
	ds_read_b128 v[16:19], v156 offset:16944
	v_add_f32_dpp v174, v174, v174 row_ror:8 row_mask:0xf bank_mask:0xf bound_ctrl:1
	v_pk_mul_f32 v[54:55], v[48:49], v[38:39] op_sel_hi:[0,1]
	v_add_f32_dpp v176, v176, v176 row_ror:8 row_mask:0xf bank_mask:0xf bound_ctrl:1
	v_pk_fma_f32 v[56:57], v[68:69], v[44:45], v[52:53]
	v_add_f32_dpp v174, v174, v174 row_ror:4 row_mask:0xf bank_mask:0xf bound_ctrl:1
	v_pk_fma_f32 v[58:59], v[70:71], v[46:47], v[54:55]
	v_add_f32_dpp v176, v176, v176 row_ror:4 row_mask:0xf bank_mask:0xf bound_ctrl:1
	v_lshl_add_u64 v[150:151], v[150:151], 0, v[64:65]
	v_add_f32_dpp v174, v174, v174 row_ror:2 row_mask:0xf bank_mask:0xf bound_ctrl:1
	v_add_u32_e32 v158, s43, v162
	v_add_f32_dpp v176, v176, v176 row_ror:2 row_mask:0xf bank_mask:0xf bound_ctrl:1
	v_add_u32_e32 v159, s43, v163
	v_add_f32_dpp v174, v174, v174 row_ror:1 row_mask:0xf bank_mask:0xf bound_ctrl:1
	v_add_f32_dpp v176, v176, v176 row_ror:1 row_mask:0xf bank_mask:0xf bound_ctrl:1
	v_pk_fma_f32 v[68:69], v[174:175], v[32:33], v[56:57] op_sel_hi:[0,1,1] neg_lo:[1,0,0] neg_hi:[1,0,0]
	v_pk_fma_f32 v[70:71], v[174:175], v[34:35], v[58:59] op_sel_hi:[0,1,1] neg_lo:[1,0,0] neg_hi:[1,0,0]
	v_cndmask_b32_e64 v60, v60, v176, s[24:25]
	s_waitcnt lgkmcnt(0)
; DEVI void rw_chain_task(const Params& p, int l, int seq, int head, int quarter, char* smem) {
;     ...
;     for (int c = 0; c < nch; c += 4) {
;       lds_barrier();
;       RW_STORE(R1, B1);
;       RW_LOAD(R1, c + 5);
;       RW_COMPUTE(B0, c);
;       lds_barrier();
;       RW_STORE(R2, B0);
;       RW_LOAD(R2, c + 6);
;       RW_COMPUTE(B1, c + 1);
;       lds_barrier();
;       RW_STORE(R3, B1);
;       RW_LOAD(R3, c + 7);
;       RW_COMPUTE(B0, c + 2);
;       lds_barrier();
;       RW_STORE(R0, B0);
;       RW_LOAD(R0, c + 8);
;       RW_COMPUTE(B1, c + 3);
;     }
	ds_read_b128 v[28:31], v156 offset:18304
	ds_read_b128 v[36:39], v156 offset:18336
	ds_read_u16_d16_hi v48, v157 offset:18304
	ds_read_b128 v[44:47], v156 offset:18368
	ds_read_b128 v[32:35], v156 offset:18320
	v_pk_mul_f32 v[172:173], v[68:69], v[4:5]
	v_pk_mul_f32 v[178:179], v[68:69], v[40:41]
	v_pk_fma_f32 v[172:173], v[70:71], v[6:7], v[172:173]
	v_pk_fma_f32 v[178:179], v[70:71], v[42:43], v[178:179]
	v_add_f32_e32 v172, v172, v173
	v_add_f32_e32 v178, v178, v179
	v_pk_mul_f32 v[52:53], v[24:25], v[12:13] op_sel_hi:[0,1]
	ds_read_b128 v[40:43], v156 offset:18352
	v_add_f32_dpp v172, v172, v172 row_ror:8 row_mask:0xf bank_mask:0xf bound_ctrl:1
	v_pk_mul_f32 v[54:55], v[24:25], v[14:15] op_sel_hi:[0,1]
	v_add_f32_dpp v178, v178, v178 row_ror:8 row_mask:0xf bank_mask:0xf bound_ctrl:1
	v_pk_fma_f32 v[56:57], v[68:69], v[20:21], v[52:53]
	v_add_f32_dpp v172, v172, v172 row_ror:4 row_mask:0xf bank_mask:0xf bound_ctrl:1
	v_pk_fma_f32 v[58:59], v[70:71], v[22:23], v[54:55]
	v_add_f32_dpp v178, v178, v178 row_ror:4 row_mask:0xf bank_mask:0xf bound_ctrl:1
	v_add_f32_dpp v172, v172, v172 row_ror:2 row_mask:0xf bank_mask:0xf bound_ctrl:1
	s_nop 0
	v_add_f32_dpp v178, v178, v178 row_ror:2 row_mask:0xf bank_mask:0xf bound_ctrl:1
	v_add_f32_dpp v172, v172, v172 row_ror:1 row_mask:0xf bank_mask:0xf bound_ctrl:1
	s_nop 0
	v_add_f32_dpp v178, v178, v178 row_ror:1 row_mask:0xf bank_mask:0xf bound_ctrl:1
	v_pk_fma_f32 v[68:69], v[172:173], v[8:9], v[56:57] op_sel_hi:[0,1,1] neg_lo:[1,0,0] neg_hi:[1,0,0]
	v_pk_fma_f32 v[70:71], v[172:173], v[10:11], v[58:59] op_sel_hi:[0,1,1] neg_lo:[1,0,0] neg_hi:[1,0,0]
	v_cndmask_b32_e64 v60, v60, v178, s[26:27]
	s_waitcnt lgkmcnt(0)
	ds_read_b128 v[4:7], v156 offset:19712
	ds_read_b128 v[12:15], v156 offset:19744
	ds_read_u16_d16_hi v24, v157 offset:19712
	ds_read_b128 v[20:23], v156 offset:19776
	ds_read_b128 v[8:11], v156 offset:19728
	v_pk_mul_f32 v[174:175], v[68:69], v[28:29]
	v_pk_mul_f32 v[176:177], v[68:69], v[16:17]
	v_pk_fma_f32 v[174:175], v[70:71], v[30:31], v[174:175]
	v_pk_fma_f32 v[176:177], v[70:71], v[18:19], v[176:177]
	v_add_f32_e32 v174, v174, v175
	v_add_f32_e32 v176, v176, v177
	v_pk_mul_f32 v[52:53], v[48:49], v[36:37] op_sel_hi:[0,1]
	ds_read_b128 v[16:19], v156 offset:19760
	v_add_f32_dpp v174, v174, v174 row_ror:8 row_mask:0xf bank_mask:0xf bound_ctrl:1
	v_pk_mul_f32 v[54:55], v[48:49], v[38:39] op_sel_hi:[0,1]
	v_add_f32_dpp v176, v176, v176 row_ror:8 row_mask:0xf bank_mask:0xf bound_ctrl:1
	v_pk_fma_f32 v[56:57], v[68:69], v[44:45], v[52:53]
	v_add_f32_dpp v174, v174, v174 row_ror:4 row_mask:0xf bank_mask:0xf bound_ctrl:1
	v_pk_fma_f32 v[58:59], v[70:71], v[46:47], v[54:55]
	v_add_f32_dpp v176, v176, v176 row_ror:4 row_mask:0xf bank_mask:0xf bound_ctrl:1
	v_add_f32_dpp v174, v174, v174 row_ror:2 row_mask:0xf bank_mask:0xf bound_ctrl:1
	s_nop 0
	v_add_f32_dpp v176, v176, v176 row_ror:2 row_mask:0xf bank_mask:0xf bound_ctrl:1
	v_add_f32_dpp v174, v174, v174 row_ror:1 row_mask:0xf bank_mask:0xf bound_ctrl:1
	s_nop 0
	v_add_f32_dpp v176, v176, v176 row_ror:1 row_mask:0xf bank_mask:0xf bound_ctrl:1
	v_pk_fma_f32 v[68:69], v[174:175], v[32:33], v[56:57] op_sel_hi:[0,1,1] neg_lo:[1,0,0] neg_hi:[1,0,0]
	v_pk_fma_f32 v[70:71], v[174:175], v[34:35], v[58:59] op_sel_hi:[0,1,1] neg_lo:[1,0,0] neg_hi:[1,0,0]
	v_cndmask_b32_e64 v60, v60, v176, s[28:29]
	s_waitcnt lgkmcnt(0)
	ds_read_b128 v[28:31], v156 offset:21120
	ds_read_b128 v[36:39], v156 offset:21152
	ds_read_u16_d16_hi v48, v157 offset:21120
	ds_read_b128 v[44:47], v156 offset:21184
	ds_read_b128 v[32:35], v156 offset:21136
	v_pk_mul_f32 v[172:173], v[68:69], v[4:5]
	v_pk_mul_f32 v[178:179], v[68:69], v[40:41]
	v_pk_fma_f32 v[172:173], v[70:71], v[6:7], v[172:173]
	v_pk_fma_f32 v[178:179], v[70:71], v[42:43], v[178:179]
	v_add_f32_e32 v172, v172, v173
	v_add_f32_e32 v178, v178, v179
	v_pk_mul_f32 v[52:53], v[24:25], v[12:13] op_sel_hi:[0,1]
	ds_read_b128 v[40:43], v156 offset:21168
	v_add_f32_dpp v172, v172, v172 row_ror:8 row_mask:0xf bank_mask:0xf bound_ctrl:1
	v_pk_mul_f32 v[54:55], v[24:25], v[14:15] op_sel_hi:[0,1]
	v_add_f32_dpp v178, v178, v178 row_ror:8 row_mask:0xf bank_mask:0xf bound_ctrl:1
	v_pk_fma_f32 v[56:57], v[68:69], v[20:21], v[52:53]
	v_add_f32_dpp v172, v172, v172 row_ror:4 row_mask:0xf bank_mask:0xf bound_ctrl:1
	v_pk_fma_f32 v[58:59], v[70:71], v[22:23], v[54:55]
	v_add_f32_dpp v178, v178, v178 row_ror:4 row_mask:0xf bank_mask:0xf bound_ctrl:1
	v_add_f32_dpp v172, v172, v172 row_ror:2 row_mask:0xf bank_mask:0xf bound_ctrl:1
	s_nop 0
	v_add_f32_dpp v178, v178, v178 row_ror:2 row_mask:0xf bank_mask:0xf bound_ctrl:1
	v_add_f32_dpp v172, v172, v172 row_ror:1 row_mask:0xf bank_mask:0xf bound_ctrl:1
	s_nop 0
	v_add_f32_dpp v178, v178, v178 row_ror:1 row_mask:0xf bank_mask:0xf bound_ctrl:1
	v_pk_fma_f32 v[68:69], v[172:173], v[8:9], v[56:57] op_sel_hi:[0,1,1] neg_lo:[1,0,0] neg_hi:[1,0,0]
	v_pk_fma_f32 v[70:71], v[172:173], v[10:11], v[58:59] op_sel_hi:[0,1,1] neg_lo:[1,0,0] neg_hi:[1,0,0]
	v_cndmask_b32_e64 v60, v60, v178, s[30:31]
	s_waitcnt lgkmcnt(0)
	ds_read_b128 v[4:7], v158 offset:0
	ds_read_b128 v[12:15], v158 offset:32
	ds_read_u16_d16_hi v24, v159 offset:0
	ds_read_b128 v[20:23], v158 offset:64
	ds_read_b128 v[8:11], v158 offset:16
	v_pk_mul_f32 v[174:175], v[68:69], v[28:29]
	v_pk_mul_f32 v[176:177], v[68:69], v[16:17]
	v_pk_fma_f32 v[174:175], v[70:71], v[30:31], v[174:175]
	v_pk_fma_f32 v[176:177], v[70:71], v[18:19], v[176:177]
	v_add_f32_e32 v174, v174, v175
	v_add_f32_e32 v176, v176, v177
	v_pk_mul_f32 v[52:53], v[48:49], v[36:37] op_sel_hi:[0,1]
	ds_read_b128 v[16:19], v158 offset:48
	v_add_f32_dpp v174, v174, v174 row_ror:8 row_mask:0xf bank_mask:0xf bound_ctrl:1
	v_pk_mul_f32 v[54:55], v[48:49], v[38:39] op_sel_hi:[0,1]
	v_add_f32_dpp v176, v176, v176 row_ror:8 row_mask:0xf bank_mask:0xf bound_ctrl:1
	v_pk_fma_f32 v[56:57], v[68:69], v[44:45], v[52:53]
	v_add_f32_dpp v174, v174, v174 row_ror:4 row_mask:0xf bank_mask:0xf bound_ctrl:1
	v_pk_fma_f32 v[58:59], v[70:71], v[46:47], v[54:55]
	v_add_f32_dpp v176, v176, v176 row_ror:4 row_mask:0xf bank_mask:0xf bound_ctrl:1
	v_add_f32_dpp v174, v174, v174 row_ror:2 row_mask:0xf bank_mask:0xf bound_ctrl:1
	s_nop 0
	v_add_f32_dpp v176, v176, v176 row_ror:2 row_mask:0xf bank_mask:0xf bound_ctrl:1
	v_add_f32_dpp v174, v174, v174 row_ror:1 row_mask:0xf bank_mask:0xf bound_ctrl:1
	s_nop 0
	v_add_f32_dpp v176, v176, v176 row_ror:1 row_mask:0xf bank_mask:0xf bound_ctrl:1
	v_pk_fma_f32 v[68:69], v[174:175], v[32:33], v[56:57] op_sel_hi:[0,1,1] neg_lo:[1,0,0] neg_hi:[1,0,0]
	v_pk_fma_f32 v[70:71], v[174:175], v[34:35], v[58:59] op_sel_hi:[0,1,1] neg_lo:[1,0,0] neg_hi:[1,0,0]
	v_cndmask_b32_e64 v60, v60, v176, s[34:35]
	s_waitcnt lgkmcnt(0)
	s_barrier
	s_mov_b32 vcc_lo, s42
	s_mov_b32 s42, s43
	s_mov_b32 s43, s45
	s_mov_b32 s45, vcc_lo
	v_add_u32_e32 v156, s42, v162
	v_add_u32_e32 v157, s42, v163
	v_add_u32_e32 v155, s45, v164
	v_add_u32_e32 v165, s45, v167
	v_add_u32_e32 v166, s45, v168
	s_waitcnt lgkmcnt(0)
	ds_read_b128 v[28:31], v156 offset:1408
	ds_read_b128 v[36:39], v156 offset:1440
	ds_read_u16_d16_hi v48, v157 offset:1408
	ds_read_b128 v[44:47], v156 offset:1472
	ds_read_b128 v[32:35], v156 offset:1424
	v_pk_mul_f32 v[172:173], v[68:69], v[4:5]
	v_pk_mul_f32 v[178:179], v[68:69], v[40:41]
	v_pk_fma_f32 v[172:173], v[70:71], v[6:7], v[172:173]
	v_pk_fma_f32 v[178:179], v[70:71], v[42:43], v[178:179]
	v_add_f32_e32 v172, v172, v173
	v_add_f32_e32 v178, v178, v179
	v_pk_mul_f32 v[52:53], v[24:25], v[12:13] op_sel_hi:[0,1]
	ds_read_b128 v[40:43], v156 offset:1456
	v_add_f32_dpp v172, v172, v172 row_ror:8 row_mask:0xf bank_mask:0xf bound_ctrl:1
	v_pk_mul_f32 v[54:55], v[24:25], v[14:15] op_sel_hi:[0,1]
	v_add_f32_dpp v178, v178, v178 row_ror:8 row_mask:0xf bank_mask:0xf bound_ctrl:1
	v_pk_fma_f32 v[56:57], v[68:69], v[20:21], v[52:53]
	v_add_f32_dpp v172, v172, v172 row_ror:4 row_mask:0xf bank_mask:0xf bound_ctrl:1
	v_pk_fma_f32 v[58:59], v[70:71], v[22:23], v[54:55]
	v_add_f32_dpp v178, v178, v178 row_ror:4 row_mask:0xf bank_mask:0xf bound_ctrl:1
	v_add_f32_dpp v172, v172, v172 row_ror:2 row_mask:0xf bank_mask:0xf bound_ctrl:1
	s_nop 0
	v_add_f32_dpp v178, v178, v178 row_ror:2 row_mask:0xf bank_mask:0xf bound_ctrl:1
	v_add_f32_dpp v172, v172, v172 row_ror:1 row_mask:0xf bank_mask:0xf bound_ctrl:1
	s_nop 0
	v_add_f32_dpp v178, v178, v178 row_ror:1 row_mask:0xf bank_mask:0xf bound_ctrl:1
	v_pk_fma_f32 v[68:69], v[172:173], v[8:9], v[56:57] op_sel_hi:[0,1,1] neg_lo:[1,0,0] neg_hi:[1,0,0]
	v_pk_fma_f32 v[70:71], v[172:173], v[10:11], v[58:59] op_sel_hi:[0,1,1] neg_lo:[1,0,0] neg_hi:[1,0,0]
	v_cndmask_b32_e64 v60, v60, v178, s[36:37]
	v_bfe_u32 v61, v60, 16, 1
	v_add3_u32 v61, v60, v61, s33
	global_store_short_d16_hi v[160:161], v61, off
	v_lshl_add_u64 v[160:161], v[160:161], 0, s[46:47]
	s_waitcnt lgkmcnt(0)
	ds_read_b128 v[4:7], v156 offset:2816
	ds_read_b128 v[12:15], v156 offset:2848
	ds_read_u16_d16_hi v24, v157 offset:2816
	ds_read_b128 v[20:23], v156 offset:2880
	ds_read_b128 v[8:11], v156 offset:2832
	v_pk_mul_f32 v[174:175], v[68:69], v[28:29]
	v_pk_mul_f32 v[176:177], v[68:69], v[16:17]
	v_pk_fma_f32 v[174:175], v[70:71], v[30:31], v[174:175]
	v_pk_fma_f32 v[176:177], v[70:71], v[18:19], v[176:177]
	v_add_f32_e32 v174, v174, v175
	v_add_f32_e32 v176, v176, v177
	v_pk_mul_f32 v[52:53], v[48:49], v[36:37] op_sel_hi:[0,1]
	ds_read_b128 v[16:19], v156 offset:2864
	v_add_f32_dpp v174, v174, v174 row_ror:8 row_mask:0xf bank_mask:0xf bound_ctrl:1
	v_pk_mul_f32 v[54:55], v[48:49], v[38:39] op_sel_hi:[0,1]
	v_add_f32_dpp v176, v176, v176 row_ror:8 row_mask:0xf bank_mask:0xf bound_ctrl:1
	v_pk_fma_f32 v[56:57], v[68:69], v[44:45], v[52:53]
	v_add_f32_dpp v174, v174, v174 row_ror:4 row_mask:0xf bank_mask:0xf bound_ctrl:1
	v_pk_fma_f32 v[58:59], v[70:71], v[46:47], v[54:55]
	v_add_f32_dpp v176, v176, v176 row_ror:4 row_mask:0xf bank_mask:0xf bound_ctrl:1
	s_waitcnt vmcnt(12)
	v_add_f32_dpp v174, v174, v174 row_ror:2 row_mask:0xf bank_mask:0xf bound_ctrl:1
	v_lshlrev_b32_e32 v136, 16, v88
	v_add_f32_dpp v176, v176, v176 row_ror:2 row_mask:0xf bank_mask:0xf bound_ctrl:1
	v_and_b32_e32 v137, 0xffff0000, v88
	v_add_f32_dpp v174, v174, v174 row_ror:1 row_mask:0xf bank_mask:0xf bound_ctrl:1
	v_add_f32_dpp v176, v176, v176 row_ror:1 row_mask:0xf bank_mask:0xf bound_ctrl:1
	v_pk_fma_f32 v[68:69], v[174:175], v[32:33], v[56:57] op_sel_hi:[0,1,1] neg_lo:[1,0,0] neg_hi:[1,0,0]
	v_pk_fma_f32 v[70:71], v[174:175], v[34:35], v[58:59] op_sel_hi:[0,1,1] neg_lo:[1,0,0] neg_hi:[1,0,0]
	v_cndmask_b32_e64 v60, v60, v176, s[4:5]
	s_waitcnt lgkmcnt(0)
	ds_read_b128 v[28:31], v156 offset:4224
	ds_read_b128 v[36:39], v156 offset:4256
	ds_read_u16_d16_hi v48, v157 offset:4224
	ds_read_b128 v[44:47], v156 offset:4288
	ds_read_b128 v[32:35], v156 offset:4240
	v_pk_mul_f32 v[172:173], v[68:69], v[4:5]
	v_pk_mul_f32 v[178:179], v[68:69], v[40:41]
	v_pk_fma_f32 v[172:173], v[70:71], v[6:7], v[172:173]
	v_pk_fma_f32 v[178:179], v[70:71], v[42:43], v[178:179]
	v_add_f32_e32 v172, v172, v173
	v_add_f32_e32 v178, v178, v179
	v_pk_mul_f32 v[52:53], v[24:25], v[12:13] op_sel_hi:[0,1]
	ds_read_b128 v[40:43], v156 offset:4272
	v_add_f32_dpp v172, v172, v172 row_ror:8 row_mask:0xf bank_mask:0xf bound_ctrl:1
	v_pk_mul_f32 v[54:55], v[24:25], v[14:15] op_sel_hi:[0,1]
	v_add_f32_dpp v178, v178, v178 row_ror:8 row_mask:0xf bank_mask:0xf bound_ctrl:1
	v_pk_fma_f32 v[56:57], v[68:69], v[20:21], v[52:53]
	v_add_f32_dpp v172, v172, v172 row_ror:4 row_mask:0xf bank_mask:0xf bound_ctrl:1
	v_pk_fma_f32 v[58:59], v[70:71], v[22:23], v[54:55]
	v_add_f32_dpp v178, v178, v178 row_ror:4 row_mask:0xf bank_mask:0xf bound_ctrl:1
	v_lshlrev_b32_e32 v138, 16, v89
	v_add_f32_dpp v172, v172, v172 row_ror:2 row_mask:0xf bank_mask:0xf bound_ctrl:1
	v_and_b32_e32 v139, 0xffff0000, v89
	v_add_f32_dpp v178, v178, v178 row_ror:2 row_mask:0xf bank_mask:0xf bound_ctrl:1
	v_lshlrev_b32_e32 v140, 16, v90
	v_add_f32_dpp v172, v172, v172 row_ror:1 row_mask:0xf bank_mask:0xf bound_ctrl:1
	v_add_f32_dpp v178, v178, v178 row_ror:1 row_mask:0xf bank_mask:0xf bound_ctrl:1
	v_pk_fma_f32 v[68:69], v[172:173], v[8:9], v[56:57] op_sel_hi:[0,1,1] neg_lo:[1,0,0] neg_hi:[1,0,0]
	v_pk_fma_f32 v[70:71], v[172:173], v[10:11], v[58:59] op_sel_hi:[0,1,1] neg_lo:[1,0,0] neg_hi:[1,0,0]
	v_cndmask_b32_e64 v60, v60, v178, s[6:7]
	s_waitcnt lgkmcnt(0)
	ds_read_b128 v[4:7], v156 offset:5632
	ds_read_b128 v[12:15], v156 offset:5664
	ds_read_u16_d16_hi v24, v157 offset:5632
	ds_read_b128 v[20:23], v156 offset:5696
	ds_read_b128 v[8:11], v156 offset:5648
	v_pk_mul_f32 v[174:175], v[68:69], v[28:29]
	v_pk_mul_f32 v[176:177], v[68:69], v[16:17]
	v_pk_fma_f32 v[174:175], v[70:71], v[30:31], v[174:175]
	v_pk_fma_f32 v[176:177], v[70:71], v[18:19], v[176:177]
	v_add_f32_e32 v174, v174, v175
	v_add_f32_e32 v176, v176, v177
	v_pk_mul_f32 v[52:53], v[48:49], v[36:37] op_sel_hi:[0,1]
	ds_read_b128 v[16:19], v156 offset:5680
	v_add_f32_dpp v174, v174, v174 row_ror:8 row_mask:0xf bank_mask:0xf bound_ctrl:1
	v_pk_mul_f32 v[54:55], v[48:49], v[38:39] op_sel_hi:[0,1]
	v_add_f32_dpp v176, v176, v176 row_ror:8 row_mask:0xf bank_mask:0xf bound_ctrl:1
	v_pk_fma_f32 v[56:57], v[68:69], v[44:45], v[52:53]
	v_add_f32_dpp v174, v174, v174 row_ror:4 row_mask:0xf bank_mask:0xf bound_ctrl:1
	v_pk_fma_f32 v[58:59], v[70:71], v[46:47], v[54:55]
	v_add_f32_dpp v176, v176, v176 row_ror:4 row_mask:0xf bank_mask:0xf bound_ctrl:1
	v_and_b32_e32 v141, 0xffff0000, v90
	v_add_f32_dpp v174, v174, v174 row_ror:2 row_mask:0xf bank_mask:0xf bound_ctrl:1
	v_lshlrev_b32_e32 v142, 16, v91
	v_add_f32_dpp v176, v176, v176 row_ror:2 row_mask:0xf bank_mask:0xf bound_ctrl:1
	v_and_b32_e32 v143, 0xffff0000, v91
	v_add_f32_dpp v174, v174, v174 row_ror:1 row_mask:0xf bank_mask:0xf bound_ctrl:1
	v_add_f32_dpp v176, v176, v176 row_ror:1 row_mask:0xf bank_mask:0xf bound_ctrl:1
	v_pk_fma_f32 v[68:69], v[174:175], v[32:33], v[56:57] op_sel_hi:[0,1,1] neg_lo:[1,0,0] neg_hi:[1,0,0]
	v_pk_fma_f32 v[70:71], v[174:175], v[34:35], v[58:59] op_sel_hi:[0,1,1] neg_lo:[1,0,0] neg_hi:[1,0,0]
	v_cndmask_b32_e64 v60, v60, v176, s[8:9]
	s_waitcnt lgkmcnt(0)
	ds_read_b128 v[28:31], v156 offset:7040
	ds_read_b128 v[36:39], v156 offset:7072
	ds_read_u16_d16_hi v48, v157 offset:7040
	ds_read_b128 v[44:47], v156 offset:7104
	ds_read_b128 v[32:35], v156 offset:7056
	v_pk_mul_f32 v[172:173], v[68:69], v[4:5]
	v_pk_mul_f32 v[178:179], v[68:69], v[40:41]
	v_pk_fma_f32 v[172:173], v[70:71], v[6:7], v[172:173]
	v_pk_fma_f32 v[178:179], v[70:71], v[42:43], v[178:179]
	v_add_f32_e32 v172, v172, v173
	v_add_f32_e32 v178, v178, v179
	v_pk_mul_f32 v[52:53], v[24:25], v[12:13] op_sel_hi:[0,1]
	ds_read_b128 v[40:43], v156 offset:7088
	v_add_f32_dpp v172, v172, v172 row_ror:8 row_mask:0xf bank_mask:0xf bound_ctrl:1
	v_pk_mul_f32 v[54:55], v[24:25], v[14:15] op_sel_hi:[0,1]
	v_add_f32_dpp v178, v178, v178 row_ror:8 row_mask:0xf bank_mask:0xf bound_ctrl:1
	v_pk_fma_f32 v[56:57], v[68:69], v[20:21], v[52:53]
	v_add_f32_dpp v172, v172, v172 row_ror:4 row_mask:0xf bank_mask:0xf bound_ctrl:1
	v_pk_fma_f32 v[58:59], v[70:71], v[22:23], v[54:55]
	v_add_f32_dpp v178, v178, v178 row_ror:4 row_mask:0xf bank_mask:0xf bound_ctrl:1
	ds_write_b128 v155, v[136:139] offset:0
	v_add_f32_dpp v172, v172, v172 row_ror:2 row_mask:0xf bank_mask:0xf bound_ctrl:1
	ds_write_b128 v155, v[140:143] offset:80
	v_add_f32_dpp v178, v178, v178 row_ror:2 row_mask:0xf bank_mask:0xf bound_ctrl:1
	v_lshlrev_b32_e32 v136, 16, v92
	v_add_f32_dpp v172, v172, v172 row_ror:1 row_mask:0xf bank_mask:0xf bound_ctrl:1
	v_add_f32_dpp v178, v178, v178 row_ror:1 row_mask:0xf bank_mask:0xf bound_ctrl:1
	v_pk_fma_f32 v[68:69], v[172:173], v[8:9], v[56:57] op_sel_hi:[0,1,1] neg_lo:[1,0,0] neg_hi:[1,0,0]
	v_pk_fma_f32 v[70:71], v[172:173], v[10:11], v[58:59] op_sel_hi:[0,1,1] neg_lo:[1,0,0] neg_hi:[1,0,0]
	v_cndmask_b32_e64 v60, v60, v178, s[10:11]
	s_waitcnt lgkmcnt(2)
	ds_read_b128 v[4:7], v156 offset:8448
	ds_read_b128 v[12:15], v156 offset:8480
	ds_read_u16_d16_hi v24, v157 offset:8448
	ds_read_b128 v[20:23], v156 offset:8512
	ds_read_b128 v[8:11], v156 offset:8464
	v_pk_mul_f32 v[174:175], v[68:69], v[28:29]
	v_pk_mul_f32 v[176:177], v[68:69], v[16:17]
	v_pk_fma_f32 v[174:175], v[70:71], v[30:31], v[174:175]
	v_pk_fma_f32 v[176:177], v[70:71], v[18:19], v[176:177]
	v_add_f32_e32 v174, v174, v175
	v_add_f32_e32 v176, v176, v177
	v_pk_mul_f32 v[52:53], v[48:49], v[36:37] op_sel_hi:[0,1]
	ds_read_b128 v[16:19], v156 offset:8496
	v_add_f32_dpp v174, v174, v174 row_ror:8 row_mask:0xf bank_mask:0xf bound_ctrl:1
	v_pk_mul_f32 v[54:55], v[48:49], v[38:39] op_sel_hi:[0,1]
	v_add_f32_dpp v176, v176, v176 row_ror:8 row_mask:0xf bank_mask:0xf bound_ctrl:1
	v_pk_fma_f32 v[56:57], v[68:69], v[44:45], v[52:53]
	v_add_f32_dpp v174, v174, v174 row_ror:4 row_mask:0xf bank_mask:0xf bound_ctrl:1
	v_pk_fma_f32 v[58:59], v[70:71], v[46:47], v[54:55]
	v_add_f32_dpp v176, v176, v176 row_ror:4 row_mask:0xf bank_mask:0xf bound_ctrl:1
	v_and_b32_e32 v137, 0xffff0000, v92
	v_add_f32_dpp v174, v174, v174 row_ror:2 row_mask:0xf bank_mask:0xf bound_ctrl:1
	v_lshlrev_b32_e32 v138, 16, v93
	v_add_f32_dpp v176, v176, v176 row_ror:2 row_mask:0xf bank_mask:0xf bound_ctrl:1
	v_and_b32_e32 v139, 0xffff0000, v93
	v_add_f32_dpp v174, v174, v174 row_ror:1 row_mask:0xf bank_mask:0xf bound_ctrl:1
	v_add_f32_dpp v176, v176, v176 row_ror:1 row_mask:0xf bank_mask:0xf bound_ctrl:1
	v_pk_fma_f32 v[68:69], v[174:175], v[32:33], v[56:57] op_sel_hi:[0,1,1] neg_lo:[1,0,0] neg_hi:[1,0,0]
	v_pk_fma_f32 v[70:71], v[174:175], v[34:35], v[58:59] op_sel_hi:[0,1,1] neg_lo:[1,0,0] neg_hi:[1,0,0]
	v_cndmask_b32_e64 v60, v60, v176, s[12:13]
	s_waitcnt lgkmcnt(0)
	ds_read_b128 v[28:31], v156 offset:9856
	ds_read_b128 v[36:39], v156 offset:9888
	ds_read_u16_d16_hi v48, v157 offset:9856
	ds_read_b128 v[44:47], v156 offset:9920
	ds_read_b128 v[32:35], v156 offset:9872
	v_pk_mul_f32 v[172:173], v[68:69], v[4:5]
	v_pk_mul_f32 v[178:179], v[68:69], v[40:41]
	v_pk_fma_f32 v[172:173], v[70:71], v[6:7], v[172:173]
	v_pk_fma_f32 v[178:179], v[70:71], v[42:43], v[178:179]
	v_add_f32_e32 v172, v172, v173
	v_add_f32_e32 v178, v178, v179
	v_pk_mul_f32 v[52:53], v[24:25], v[12:13] op_sel_hi:[0,1]
	ds_read_b128 v[40:43], v156 offset:9904
	v_add_f32_dpp v172, v172, v172 row_ror:8 row_mask:0xf bank_mask:0xf bound_ctrl:1
	v_pk_mul_f32 v[54:55], v[24:25], v[14:15] op_sel_hi:[0,1]
	v_add_f32_dpp v178, v178, v178 row_ror:8 row_mask:0xf bank_mask:0xf bound_ctrl:1
	v_pk_fma_f32 v[56:57], v[68:69], v[20:21], v[52:53]
	v_add_f32_dpp v172, v172, v172 row_ror:4 row_mask:0xf bank_mask:0xf bound_ctrl:1
	v_pk_fma_f32 v[58:59], v[70:71], v[22:23], v[54:55]
	v_add_f32_dpp v178, v178, v178 row_ror:4 row_mask:0xf bank_mask:0xf bound_ctrl:1
	v_lshlrev_b32_e32 v140, 16, v94
	v_add_f32_dpp v172, v172, v172 row_ror:2 row_mask:0xf bank_mask:0xf bound_ctrl:1
	v_and_b32_e32 v141, 0xffff0000, v94
	v_add_f32_dpp v178, v178, v178 row_ror:2 row_mask:0xf bank_mask:0xf bound_ctrl:1
	v_lshlrev_b32_e32 v142, 16, v95
	v_add_f32_dpp v172, v172, v172 row_ror:1 row_mask:0xf bank_mask:0xf bound_ctrl:1
	v_add_f32_dpp v178, v178, v178 row_ror:1 row_mask:0xf bank_mask:0xf bound_ctrl:1
	v_pk_fma_f32 v[68:69], v[172:173], v[8:9], v[56:57] op_sel_hi:[0,1,1] neg_lo:[1,0,0] neg_hi:[1,0,0]
	v_pk_fma_f32 v[70:71], v[172:173], v[10:11], v[58:59] op_sel_hi:[0,1,1] neg_lo:[1,0,0] neg_hi:[1,0,0]
	v_cndmask_b32_e64 v60, v60, v178, s[14:15]
	s_waitcnt lgkmcnt(0)
	ds_read_b128 v[4:7], v156 offset:11264
	ds_read_b128 v[12:15], v156 offset:11296
	ds_read_u16_d16_hi v24, v157 offset:11264
	ds_read_b128 v[20:23], v156 offset:11328
	ds_read_b128 v[8:11], v156 offset:11280
	v_pk_mul_f32 v[174:175], v[68:69], v[28:29]
	v_pk_mul_f32 v[176:177], v[68:69], v[16:17]
	v_pk_fma_f32 v[174:175], v[70:71], v[30:31], v[174:175]
	v_pk_fma_f32 v[176:177], v[70:71], v[18:19], v[176:177]
	v_add_f32_e32 v174, v174, v175
	v_add_f32_e32 v176, v176, v177
	v_pk_mul_f32 v[52:53], v[48:49], v[36:37] op_sel_hi:[0,1]
	ds_read_b128 v[16:19], v156 offset:11312
	v_add_f32_dpp v174, v174, v174 row_ror:8 row_mask:0xf bank_mask:0xf bound_ctrl:1
	v_pk_mul_f32 v[54:55], v[48:49], v[38:39] op_sel_hi:[0,1]
	v_add_f32_dpp v176, v176, v176 row_ror:8 row_mask:0xf bank_mask:0xf bound_ctrl:1
	v_pk_fma_f32 v[56:57], v[68:69], v[44:45], v[52:53]
	v_add_f32_dpp v174, v174, v174 row_ror:4 row_mask:0xf bank_mask:0xf bound_ctrl:1
	v_pk_fma_f32 v[58:59], v[70:71], v[46:47], v[54:55]
	v_add_f32_dpp v176, v176, v176 row_ror:4 row_mask:0xf bank_mask:0xf bound_ctrl:1
	v_and_b32_e32 v143, 0xffff0000, v95
	v_add_f32_dpp v174, v174, v174 row_ror:2 row_mask:0xf bank_mask:0xf bound_ctrl:1
	ds_write_b128 v155, v[136:139] offset:11264
	v_add_f32_dpp v176, v176, v176 row_ror:2 row_mask:0xf bank_mask:0xf bound_ctrl:1
	ds_write_b128 v155, v[140:143] offset:11344
	v_add_f32_dpp v174, v174, v174 row_ror:1 row_mask:0xf bank_mask:0xf bound_ctrl:1
	v_add_f32_dpp v176, v176, v176 row_ror:1 row_mask:0xf bank_mask:0xf bound_ctrl:1
	v_pk_fma_f32 v[68:69], v[174:175], v[32:33], v[56:57] op_sel_hi:[0,1,1] neg_lo:[1,0,0] neg_hi:[1,0,0]
	v_pk_fma_f32 v[70:71], v[174:175], v[34:35], v[58:59] op_sel_hi:[0,1,1] neg_lo:[1,0,0] neg_hi:[1,0,0]
	v_cndmask_b32_e64 v60, v60, v176, s[16:17]
	s_waitcnt lgkmcnt(2)
	ds_read_b128 v[28:31], v156 offset:12672
	ds_read_b128 v[36:39], v156 offset:12704
	ds_read_u16_d16_hi v48, v157 offset:12672
	ds_read_b128 v[44:47], v156 offset:12736
	ds_read_b128 v[32:35], v156 offset:12688
	v_pk_mul_f32 v[172:173], v[68:69], v[4:5]
	v_pk_mul_f32 v[178:179], v[68:69], v[40:41]
	v_pk_fma_f32 v[172:173], v[70:71], v[6:7], v[172:173]
	v_pk_fma_f32 v[178:179], v[70:71], v[42:43], v[178:179]
	v_add_f32_e32 v172, v172, v173
	v_add_f32_e32 v178, v178, v179
	v_pk_mul_f32 v[52:53], v[24:25], v[12:13] op_sel_hi:[0,1]
	ds_read_b128 v[40:43], v156 offset:12720
	v_add_f32_dpp v172, v172, v172 row_ror:8 row_mask:0xf bank_mask:0xf bound_ctrl:1
	v_pk_mul_f32 v[54:55], v[24:25], v[14:15] op_sel_hi:[0,1]
	v_add_f32_dpp v178, v178, v178 row_ror:8 row_mask:0xf bank_mask:0xf bound_ctrl:1
	v_pk_fma_f32 v[56:57], v[68:69], v[20:21], v[52:53]
	v_add_f32_dpp v172, v172, v172 row_ror:4 row_mask:0xf bank_mask:0xf bound_ctrl:1
	v_pk_fma_f32 v[58:59], v[70:71], v[22:23], v[54:55]
	v_add_f32_dpp v178, v178, v178 row_ror:4 row_mask:0xf bank_mask:0xf bound_ctrl:1
	ds_write_b128 v165, v[96:99]
	v_add_f32_dpp v172, v172, v172 row_ror:2 row_mask:0xf bank_mask:0xf bound_ctrl:1
	ds_write_b128 v166, v[100:103]
	v_add_f32_dpp v178, v178, v178 row_ror:2 row_mask:0xf bank_mask:0xf bound_ctrl:1
	global_load_dwordx4 v[88:91], v[144:145], off
	v_add_f32_dpp v172, v172, v172 row_ror:1 row_mask:0xf bank_mask:0xf bound_ctrl:1
	v_add_f32_dpp v178, v178, v178 row_ror:1 row_mask:0xf bank_mask:0xf bound_ctrl:1
	v_pk_fma_f32 v[68:69], v[172:173], v[8:9], v[56:57] op_sel_hi:[0,1,1] neg_lo:[1,0,0] neg_hi:[1,0,0]
	v_pk_fma_f32 v[70:71], v[172:173], v[10:11], v[58:59] op_sel_hi:[0,1,1] neg_lo:[1,0,0] neg_hi:[1,0,0]
	v_cndmask_b32_e64 v60, v60, v178, s[18:19]
	s_waitcnt lgkmcnt(2)
	ds_read_b128 v[4:7], v156 offset:14080
	ds_read_b128 v[12:15], v156 offset:14112
	ds_read_u16_d16_hi v24, v157 offset:14080
	ds_read_b128 v[20:23], v156 offset:14144
	ds_read_b128 v[8:11], v156 offset:14096
	v_pk_mul_f32 v[174:175], v[68:69], v[28:29]
	v_pk_mul_f32 v[176:177], v[68:69], v[16:17]
	v_pk_fma_f32 v[174:175], v[70:71], v[30:31], v[174:175]
	v_pk_fma_f32 v[176:177], v[70:71], v[18:19], v[176:177]
	v_add_f32_e32 v174, v174, v175
	v_add_f32_e32 v176, v176, v177
	v_pk_mul_f32 v[52:53], v[48:49], v[36:37] op_sel_hi:[0,1]
	ds_read_b128 v[16:19], v156 offset:14128
	v_add_f32_dpp v174, v174, v174 row_ror:8 row_mask:0xf bank_mask:0xf bound_ctrl:1
	v_pk_mul_f32 v[54:55], v[48:49], v[38:39] op_sel_hi:[0,1]
	v_add_f32_dpp v176, v176, v176 row_ror:8 row_mask:0xf bank_mask:0xf bound_ctrl:1
	v_pk_fma_f32 v[56:57], v[68:69], v[44:45], v[52:53]
	v_add_f32_dpp v174, v174, v174 row_ror:4 row_mask:0xf bank_mask:0xf bound_ctrl:1
	v_pk_fma_f32 v[58:59], v[70:71], v[46:47], v[54:55]
	v_add_f32_dpp v176, v176, v176 row_ror:4 row_mask:0xf bank_mask:0xf bound_ctrl:1
	global_load_dwordx4 v[92:95], v[146:147], off
	v_add_f32_dpp v174, v174, v174 row_ror:2 row_mask:0xf bank_mask:0xf bound_ctrl:1
	global_load_dwordx4 v[96:99], v[148:149], off
	v_add_f32_dpp v176, v176, v176 row_ror:2 row_mask:0xf bank_mask:0xf bound_ctrl:1
	global_load_dwordx4 v[100:103], v[150:151], off
	v_add_f32_dpp v174, v174, v174 row_ror:1 row_mask:0xf bank_mask:0xf bound_ctrl:1
	v_add_f32_dpp v176, v176, v176 row_ror:1 row_mask:0xf bank_mask:0xf bound_ctrl:1
	v_pk_fma_f32 v[68:69], v[174:175], v[32:33], v[56:57] op_sel_hi:[0,1,1] neg_lo:[1,0,0] neg_hi:[1,0,0]
	v_pk_fma_f32 v[70:71], v[174:175], v[34:35], v[58:59] op_sel_hi:[0,1,1] neg_lo:[1,0,0] neg_hi:[1,0,0]
	v_cndmask_b32_e64 v60, v60, v176, s[20:21]
	s_waitcnt lgkmcnt(0)
	ds_read_b128 v[28:31], v156 offset:15488
	ds_read_b128 v[36:39], v156 offset:15520
	ds_read_u16_d16_hi v48, v157 offset:15488
	ds_read_b128 v[44:47], v156 offset:15552
	ds_read_b128 v[32:35], v156 offset:15504
	v_pk_mul_f32 v[172:173], v[68:69], v[4:5]
	v_pk_mul_f32 v[178:179], v[68:69], v[40:41]
	v_pk_fma_f32 v[172:173], v[70:71], v[6:7], v[172:173]
	v_pk_fma_f32 v[178:179], v[70:71], v[42:43], v[178:179]
	v_add_f32_e32 v172, v172, v173
	v_add_f32_e32 v178, v178, v179
	v_pk_mul_f32 v[52:53], v[24:25], v[12:13] op_sel_hi:[0,1]
	ds_read_b128 v[40:43], v156 offset:15536
	v_add_f32_dpp v172, v172, v172 row_ror:8 row_mask:0xf bank_mask:0xf bound_ctrl:1
	v_pk_mul_f32 v[54:55], v[24:25], v[14:15] op_sel_hi:[0,1]
	v_add_f32_dpp v178, v178, v178 row_ror:8 row_mask:0xf bank_mask:0xf bound_ctrl:1
	v_pk_fma_f32 v[56:57], v[68:69], v[20:21], v[52:53]
	v_add_f32_dpp v172, v172, v172 row_ror:4 row_mask:0xf bank_mask:0xf bound_ctrl:1
	v_pk_fma_f32 v[58:59], v[70:71], v[22:23], v[54:55]
	v_add_f32_dpp v178, v178, v178 row_ror:4 row_mask:0xf bank_mask:0xf bound_ctrl:1
	v_lshl_add_u64 v[144:145], v[144:145], 0, v[152:153]
	v_add_f32_dpp v172, v172, v172 row_ror:2 row_mask:0xf bank_mask:0xf bound_ctrl:1
	v_lshl_add_u64 v[146:147], v[146:147], 0, v[152:153]
	v_add_f32_dpp v178, v178, v178 row_ror:2 row_mask:0xf bank_mask:0xf bound_ctrl:1
	v_lshl_add_u64 v[148:149], v[148:149], 0, v[62:63]
	v_add_f32_dpp v172, v172, v172 row_ror:1 row_mask:0xf bank_mask:0xf bound_ctrl:1
	v_add_f32_dpp v178, v178, v178 row_ror:1 row_mask:0xf bank_mask:0xf bound_ctrl:1
	v_pk_fma_f32 v[68:69], v[172:173], v[8:9], v[56:57] op_sel_hi:[0,1,1] neg_lo:[1,0,0] neg_hi:[1,0,0]
	v_pk_fma_f32 v[70:71], v[172:173], v[10:11], v[58:59] op_sel_hi:[0,1,1] neg_lo:[1,0,0] neg_hi:[1,0,0]
	v_cndmask_b32_e64 v60, v60, v178, s[22:23]
	s_waitcnt lgkmcnt(0)
	ds_read_b128 v[4:7], v156 offset:16896
	ds_read_b128 v[12:15], v156 offset:16928
	ds_read_u16_d16_hi v24, v157 offset:16896
	ds_read_b128 v[20:23], v156 offset:16960
	ds_read_b128 v[8:11], v156 offset:16912
	v_pk_mul_f32 v[174:175], v[68:69], v[28:29]
	v_pk_mul_f32 v[176:177], v[68:69], v[16:17]
	v_pk_fma_f32 v[174:175], v[70:71], v[30:31], v[174:175]
	v_pk_fma_f32 v[176:177], v[70:71], v[18:19], v[176:177]
	v_add_f32_e32 v174, v174, v175
	v_add_f32_e32 v176, v176, v177
	v_pk_mul_f32 v[52:53], v[48:49], v[36:37] op_sel_hi:[0,1]
	ds_read_b128 v[16:19], v156 offset:16944
	v_add_f32_dpp v174, v174, v174 row_ror:8 row_mask:0xf bank_mask:0xf bound_ctrl:1
	v_pk_mul_f32 v[54:55], v[48:49], v[38:39] op_sel_hi:[0,1]
	v_add_f32_dpp v176, v176, v176 row_ror:8 row_mask:0xf bank_mask:0xf bound_ctrl:1
	v_pk_fma_f32 v[56:57], v[68:69], v[44:45], v[52:53]
	v_add_f32_dpp v174, v174, v174 row_ror:4 row_mask:0xf bank_mask:0xf bound_ctrl:1
	v_pk_fma_f32 v[58:59], v[70:71], v[46:47], v[54:55]
	v_add_f32_dpp v176, v176, v176 row_ror:4 row_mask:0xf bank_mask:0xf bound_ctrl:1
	v_lshl_add_u64 v[150:151], v[150:151], 0, v[64:65]
	v_add_f32_dpp v174, v174, v174 row_ror:2 row_mask:0xf bank_mask:0xf bound_ctrl:1
	v_add_u32_e32 v158, s43, v162
	v_add_f32_dpp v176, v176, v176 row_ror:2 row_mask:0xf bank_mask:0xf bound_ctrl:1
	v_add_u32_e32 v159, s43, v163
	v_add_f32_dpp v174, v174, v174 row_ror:1 row_mask:0xf bank_mask:0xf bound_ctrl:1
	v_add_f32_dpp v176, v176, v176 row_ror:1 row_mask:0xf bank_mask:0xf bound_ctrl:1
	v_pk_fma_f32 v[68:69], v[174:175], v[32:33], v[56:57] op_sel_hi:[0,1,1] neg_lo:[1,0,0] neg_hi:[1,0,0]
	v_pk_fma_f32 v[70:71], v[174:175], v[34:35], v[58:59] op_sel_hi:[0,1,1] neg_lo:[1,0,0] neg_hi:[1,0,0]
	v_cndmask_b32_e64 v60, v60, v176, s[24:25]
	s_waitcnt lgkmcnt(0)
; DEVI void rw_chain_task(const Params& p, int l, int seq, int head, int quarter, char* smem) {
;     ...
;     for (int c = 0; c < nch; c += 4) {
;       lds_barrier();
;       RW_STORE(R1, B1);
;       RW_LOAD(R1, c + 5);
;       RW_COMPUTE(B0, c);
;       lds_barrier();
;       RW_STORE(R2, B0);
;       RW_LOAD(R2, c + 6);
;       RW_COMPUTE(B1, c + 1);
;       lds_barrier();
;       RW_STORE(R3, B1);
;       RW_LOAD(R3, c + 7);
;       RW_COMPUTE(B0, c + 2);
;       lds_barrier();
;       RW_STORE(R0, B0);
;       RW_LOAD(R0, c + 8);
;       RW_COMPUTE(B1, c + 3);
;     }
	ds_read_b128 v[28:31], v156 offset:18304
	ds_read_b128 v[36:39], v156 offset:18336
	ds_read_u16_d16_hi v48, v157 offset:18304
	ds_read_b128 v[44:47], v156 offset:18368
	ds_read_b128 v[32:35], v156 offset:18320
	v_pk_mul_f32 v[172:173], v[68:69], v[4:5]
	v_pk_mul_f32 v[178:179], v[68:69], v[40:41]
	v_pk_fma_f32 v[172:173], v[70:71], v[6:7], v[172:173]
	v_pk_fma_f32 v[178:179], v[70:71], v[42:43], v[178:179]
	v_add_f32_e32 v172, v172, v173
	v_add_f32_e32 v178, v178, v179
	v_pk_mul_f32 v[52:53], v[24:25], v[12:13] op_sel_hi:[0,1]
	ds_read_b128 v[40:43], v156 offset:18352
	v_add_f32_dpp v172, v172, v172 row_ror:8 row_mask:0xf bank_mask:0xf bound_ctrl:1
	v_pk_mul_f32 v[54:55], v[24:25], v[14:15] op_sel_hi:[0,1]
	v_add_f32_dpp v178, v178, v178 row_ror:8 row_mask:0xf bank_mask:0xf bound_ctrl:1
	v_pk_fma_f32 v[56:57], v[68:69], v[20:21], v[52:53]
	v_add_f32_dpp v172, v172, v172 row_ror:4 row_mask:0xf bank_mask:0xf bound_ctrl:1
	v_pk_fma_f32 v[58:59], v[70:71], v[22:23], v[54:55]
	v_add_f32_dpp v178, v178, v178 row_ror:4 row_mask:0xf bank_mask:0xf bound_ctrl:1
	v_add_f32_dpp v172, v172, v172 row_ror:2 row_mask:0xf bank_mask:0xf bound_ctrl:1
	s_nop 0
	v_add_f32_dpp v178, v178, v178 row_ror:2 row_mask:0xf bank_mask:0xf bound_ctrl:1
	v_add_f32_dpp v172, v172, v172 row_ror:1 row_mask:0xf bank_mask:0xf bound_ctrl:1
	s_nop 0
	v_add_f32_dpp v178, v178, v178 row_ror:1 row_mask:0xf bank_mask:0xf bound_ctrl:1
	v_pk_fma_f32 v[68:69], v[172:173], v[8:9], v[56:57] op_sel_hi:[0,1,1] neg_lo:[1,0,0] neg_hi:[1,0,0]
	v_pk_fma_f32 v[70:71], v[172:173], v[10:11], v[58:59] op_sel_hi:[0,1,1] neg_lo:[1,0,0] neg_hi:[1,0,0]
	v_cndmask_b32_e64 v60, v60, v178, s[26:27]
	s_waitcnt lgkmcnt(0)
	ds_read_b128 v[4:7], v156 offset:19712
	ds_read_b128 v[12:15], v156 offset:19744
	ds_read_u16_d16_hi v24, v157 offset:19712
	ds_read_b128 v[20:23], v156 offset:19776
	ds_read_b128 v[8:11], v156 offset:19728
	v_pk_mul_f32 v[174:175], v[68:69], v[28:29]
	v_pk_mul_f32 v[176:177], v[68:69], v[16:17]
	v_pk_fma_f32 v[174:175], v[70:71], v[30:31], v[174:175]
	v_pk_fma_f32 v[176:177], v[70:71], v[18:19], v[176:177]
	v_add_f32_e32 v174, v174, v175
	v_add_f32_e32 v176, v176, v177
	v_pk_mul_f32 v[52:53], v[48:49], v[36:37] op_sel_hi:[0,1]
	ds_read_b128 v[16:19], v156 offset:19760
	v_add_f32_dpp v174, v174, v174 row_ror:8 row_mask:0xf bank_mask:0xf bound_ctrl:1
	v_pk_mul_f32 v[54:55], v[48:49], v[38:39] op_sel_hi:[0,1]
	v_add_f32_dpp v176, v176, v176 row_ror:8 row_mask:0xf bank_mask:0xf bound_ctrl:1
	v_pk_fma_f32 v[56:57], v[68:69], v[44:45], v[52:53]
	v_add_f32_dpp v174, v174, v174 row_ror:4 row_mask:0xf bank_mask:0xf bound_ctrl:1
	v_pk_fma_f32 v[58:59], v[70:71], v[46:47], v[54:55]
	v_add_f32_dpp v176, v176, v176 row_ror:4 row_mask:0xf bank_mask:0xf bound_ctrl:1
	v_add_f32_dpp v174, v174, v174 row_ror:2 row_mask:0xf bank_mask:0xf bound_ctrl:1
	s_nop 0
	v_add_f32_dpp v176, v176, v176 row_ror:2 row_mask:0xf bank_mask:0xf bound_ctrl:1
	v_add_f32_dpp v174, v174, v174 row_ror:1 row_mask:0xf bank_mask:0xf bound_ctrl:1
	s_nop 0
	v_add_f32_dpp v176, v176, v176 row_ror:1 row_mask:0xf bank_mask:0xf bound_ctrl:1
	v_pk_fma_f32 v[68:69], v[174:175], v[32:33], v[56:57] op_sel_hi:[0,1,1] neg_lo:[1,0,0] neg_hi:[1,0,0]
	v_pk_fma_f32 v[70:71], v[174:175], v[34:35], v[58:59] op_sel_hi:[0,1,1] neg_lo:[1,0,0] neg_hi:[1,0,0]
	v_cndmask_b32_e64 v60, v60, v176, s[28:29]
	s_waitcnt lgkmcnt(0)
	ds_read_b128 v[28:31], v156 offset:21120
	ds_read_b128 v[36:39], v156 offset:21152
	ds_read_u16_d16_hi v48, v157 offset:21120
	ds_read_b128 v[44:47], v156 offset:21184
	ds_read_b128 v[32:35], v156 offset:21136
	v_pk_mul_f32 v[172:173], v[68:69], v[4:5]
	v_pk_mul_f32 v[178:179], v[68:69], v[40:41]
	v_pk_fma_f32 v[172:173], v[70:71], v[6:7], v[172:173]
	v_pk_fma_f32 v[178:179], v[70:71], v[42:43], v[178:179]
	v_add_f32_e32 v172, v172, v173
	v_add_f32_e32 v178, v178, v179
	v_pk_mul_f32 v[52:53], v[24:25], v[12:13] op_sel_hi:[0,1]
	ds_read_b128 v[40:43], v156 offset:21168
	v_add_f32_dpp v172, v172, v172 row_ror:8 row_mask:0xf bank_mask:0xf bound_ctrl:1
	v_pk_mul_f32 v[54:55], v[24:25], v[14:15] op_sel_hi:[0,1]
	v_add_f32_dpp v178, v178, v178 row_ror:8 row_mask:0xf bank_mask:0xf bound_ctrl:1
	v_pk_fma_f32 v[56:57], v[68:69], v[20:21], v[52:53]
	v_add_f32_dpp v172, v172, v172 row_ror:4 row_mask:0xf bank_mask:0xf bound_ctrl:1
	v_pk_fma_f32 v[58:59], v[70:71], v[22:23], v[54:55]
	v_add_f32_dpp v178, v178, v178 row_ror:4 row_mask:0xf bank_mask:0xf bound_ctrl:1
	v_add_f32_dpp v172, v172, v172 row_ror:2 row_mask:0xf bank_mask:0xf bound_ctrl:1
	s_nop 0
	v_add_f32_dpp v178, v178, v178 row_ror:2 row_mask:0xf bank_mask:0xf bound_ctrl:1
	v_add_f32_dpp v172, v172, v172 row_ror:1 row_mask:0xf bank_mask:0xf bound_ctrl:1
	s_nop 0
	v_add_f32_dpp v178, v178, v178 row_ror:1 row_mask:0xf bank_mask:0xf bound_ctrl:1
	v_pk_fma_f32 v[68:69], v[172:173], v[8:9], v[56:57] op_sel_hi:[0,1,1] neg_lo:[1,0,0] neg_hi:[1,0,0]
	v_pk_fma_f32 v[70:71], v[172:173], v[10:11], v[58:59] op_sel_hi:[0,1,1] neg_lo:[1,0,0] neg_hi:[1,0,0]
	v_cndmask_b32_e64 v60, v60, v178, s[30:31]
	s_waitcnt lgkmcnt(0)
	ds_read_b128 v[4:7], v158 offset:0
	ds_read_b128 v[12:15], v158 offset:32
	ds_read_u16_d16_hi v24, v159 offset:0
	ds_read_b128 v[20:23], v158 offset:64
	ds_read_b128 v[8:11], v158 offset:16
	v_pk_mul_f32 v[174:175], v[68:69], v[28:29]
	v_pk_mul_f32 v[176:177], v[68:69], v[16:17]
	v_pk_fma_f32 v[174:175], v[70:71], v[30:31], v[174:175]
	v_pk_fma_f32 v[176:177], v[70:71], v[18:19], v[176:177]
	v_add_f32_e32 v174, v174, v175
	v_add_f32_e32 v176, v176, v177
	v_pk_mul_f32 v[52:53], v[48:49], v[36:37] op_sel_hi:[0,1]
	ds_read_b128 v[16:19], v158 offset:48
	v_add_f32_dpp v174, v174, v174 row_ror:8 row_mask:0xf bank_mask:0xf bound_ctrl:1
	v_pk_mul_f32 v[54:55], v[48:49], v[38:39] op_sel_hi:[0,1]
	v_add_f32_dpp v176, v176, v176 row_ror:8 row_mask:0xf bank_mask:0xf bound_ctrl:1
	v_pk_fma_f32 v[56:57], v[68:69], v[44:45], v[52:53]
	v_add_f32_dpp v174, v174, v174 row_ror:4 row_mask:0xf bank_mask:0xf bound_ctrl:1
	v_pk_fma_f32 v[58:59], v[70:71], v[46:47], v[54:55]
	v_add_f32_dpp v176, v176, v176 row_ror:4 row_mask:0xf bank_mask:0xf bound_ctrl:1
	v_add_f32_dpp v174, v174, v174 row_ror:2 row_mask:0xf bank_mask:0xf bound_ctrl:1
	s_nop 0
	v_add_f32_dpp v176, v176, v176 row_ror:2 row_mask:0xf bank_mask:0xf bound_ctrl:1
	v_add_f32_dpp v174, v174, v174 row_ror:1 row_mask:0xf bank_mask:0xf bound_ctrl:1
	s_nop 0
	v_add_f32_dpp v176, v176, v176 row_ror:1 row_mask:0xf bank_mask:0xf bound_ctrl:1
	v_pk_fma_f32 v[68:69], v[174:175], v[32:33], v[56:57] op_sel_hi:[0,1,1] neg_lo:[1,0,0] neg_hi:[1,0,0]
	v_pk_fma_f32 v[70:71], v[174:175], v[34:35], v[58:59] op_sel_hi:[0,1,1] neg_lo:[1,0,0] neg_hi:[1,0,0]
	v_cndmask_b32_e64 v60, v60, v176, s[34:35]
	s_add_u32 s41, s41, 4
	s_cmpk_lt_u32 s41, 0x400
	s_cbranch_scc1 .Lrwc_loop
; DEVI void rw_chain_task(const Params& p, int l, int seq, int head, int quarter, char* smem) {
;     ...
;   __syncthreads();
;     ...
;   float* so = seq < 2 ? p.out + O_PRWS + ((((size_t)l * 2 + seq) * 12 + head) * 64 + i) * 64 + jl * 4
;                       : p.out + O_SRWS + ((((size_t)l * 8 + (seq - 2)) * 12 + head) * 64 + i) * 64 + jl * 4;
;   *(float4*)so = make_float4(S[0], S[1], S[2], S[3]);
	s_waitcnt lgkmcnt(0)
	v_pk_mul_f32 v[178:179], v[68:69], v[40:41]
	v_pk_fma_f32 v[178:179], v[70:71], v[42:43], v[178:179]
	v_add_f32_e32 v178, v178, v179
	s_nop 1
	v_add_f32_dpp v178, v178, v178 row_ror:8 row_mask:0xf bank_mask:0xf bound_ctrl:1
	s_nop 1
	v_add_f32_dpp v178, v178, v178 row_ror:4 row_mask:0xf bank_mask:0xf bound_ctrl:1
	s_nop 1
	v_add_f32_dpp v178, v178, v178 row_ror:2 row_mask:0xf bank_mask:0xf bound_ctrl:1
	s_nop 1
	v_add_f32_dpp v178, v178, v178 row_ror:1 row_mask:0xf bank_mask:0xf bound_ctrl:1
	s_nop 0
	v_cndmask_b32_e64 v60, v60, v178, s[36:37]
	v_bfe_u32 v61, v60, 16, 1
	v_add3_u32 v61, v60, v61, s33
	global_store_short_d16_hi v[160:161], v61, off
	s_waitcnt vmcnt(0)
	s_movk_i32 s41, 0x3fc
	s_mov_b32 s42, 0xffff0000
	s_mov_b32 s43, 0xfffd0000
	s_mov_b32 s45, 0xfffe0000
	s_mov_b64 s[46:47], 0x40000
	v_readlane_b32 s38, v253, 39
	v_readlane_b32 s39, v253, 40
	v_and_b32_e32 v136, 16, v1
	v_cmp_eq_u32_e32 vcc, 0, v136
	v_readlane_b32 s4, v254, 2
	s_lshl_b32 s4, s4, 1
	v_readlane_b32 s6, v253, 37
	v_readlane_b32 s5, v254, 3
	v_readlane_b32 s7, v253, 38
	s_add_u32 s4, s4, s6
	s_addc_u32 s5, 0, s7
	s_mul_i32 s5, s5, 12
	s_mul_hi_u32 s6, s4, 12
	s_add_i32 s6, s6, s5
	s_mul_i32 s4, s4, 12
	v_readlane_b32 s5, v253, 4
	s_add_u32 s4, s4, s5
	v_readlane_b32 s5, v253, 5
	s_addc_u32 s5, s6, s5
	s_lshl_b64 s[4:5], s[4:5], 14
	v_readlane_b32 s6, v253, 2
	v_ashrrev_i32_e32 v155, 31, v154
	s_add_u32 s4, s6, s4
	v_readlane_b32 s6, v253, 3
	s_addc_u32 s5, s6, s5
	s_waitcnt vmcnt(19)
	v_lshlrev_b64 v[4:5], 8, v[154:155]
	v_lshl_add_u64 v[4:5], s[4:5], 0, v[4:5]
	v_lshlrev_b32_e32 v6, 4, v3
	v_mov_b32_e32 v7, v2
	v_lshl_add_u64 v[4:5], v[4:5], 0, v[6:7]
	s_barrier
	global_store_dwordx4 v[4:5], v[68:71], off
	s_and_b64 vcc, exec, s[2:3]
	s_cbranch_vccnz .LBB0_1001
